# MFMA pairs grouped by shared A-fragment registers across both column halves (on top of v022)
# speedup vs baseline: 1.0061x; 1.0061x over previous
; #define PG8_STAGE(bufoff, gbase, voff) do { _Pragma("unroll") for (int _i = 0; _i < 2; ++_i) \
;         __builtin_amdgcn_global_load_lds((const unsigned*)((const char*)(gbase) + (voff)[_i]), (LAS unsigned*)(lds + (bufoff) + ldsw + _i * 8192), 16, 0, 0); } while (0)
; #define PG8_LDA(dst, b, h) do { _Pragma("unroll") for (int m = 0; m < 4; ++m) _Pragma("unroll") for (int k = 0; k < 2; ++k) dst[m][k] = *(const LAS bf16x8*)(lds + PG8_SA(b, h) + aoff + m * 2048 + k * 1024); } while (0)
; #define PG8_LDB(dst, b, h) do { _Pragma("unroll") for (int n = 0; n < 2; ++n) _Pragma("unroll") for (int k = 0; k < 2; ++k) dst[n][k] = *(const LAS bf16x8*)(lds + PG8_SB(b, h) + boff + n * 2048 + k * 1024); } while (0)
; #define PG8_MMA(ai, bj, At, Bt) do { __builtin_amdgcn_s_setprio(1); _Pragma("unroll") for (int m = 0; m < 4; ++m) _Pragma("unroll") for (int n = 0; n < 2; ++n) _Pragma("unroll") for (int k = 0; k < 2; ++k) \
;         acc[ai][bj][m][n] = __builtin_amdgcn_mfma_f32_16x16x32_bf16(Bt[n][k], At[m][k], acc[ai][bj][m][n], 0, 0, 0); __builtin_amdgcn_s_setprio(0); } while (0)
; #define PG8_WAIT_V(n) asm volatile("s_waitcnt vmcnt(" #n ")" ::: "memory")
; #define PG8_WAIT_L(n) asm volatile("s_waitcnt lgkmcnt(" #n ")" ::: "memory")
; template <bool ALIGN_EPI, class Epi, class Sched>
; __device__ __forceinline__ void gemm_phase(LAS unsigned char* lds, const int lda, const int ldb, const int K, const Sched& S, const Epi& E, const size_t kstepA = (size_t)(BK * 2), const size_t kstepB = (size_t)(BK * 2)) {
;     ...
;         for (int t = 0; t < nt; t += 2) {
;             const bool last = (t == nt - 2);
;             const char* a1 = cA + (size_t)(t + 1) * kstepA;
;             const char* a2 = last ? nA : cA + (size_t)(t + 2) * kstepA; const char* b2 = last ? nB : cB + (size_t)(t + 2) * kstep;
;             const char* a3 = a2 + kstepA; const char* b3 = b2 + kstep;
;             PG8_LDB(B0, 0, 0); PG8_LDB(B1, 0, 1); PG8_SCHED; PG8_LDA(At, 0, 0); PG8_STAGE(PG8_SA(1, 1), a1 + hstepA, voffA);
;             PG8_WAIT_V(8); PG8_WAIT_L(0); PG8_BAR; PG8_MMA(0, 0, At, B0); PG8_MMA(0, 1, At, B1); PG8_BAR; PG8_SCHED;
;             PG8_LDA(At, 0, 1); PG8_STAGE(PG8_SB(0, 0), b2, voffB); PG8_STAGE(PG8_SB(0, 1), b2 + hstepB, voffB); PG8_STAGE(PG8_SA(0, 0), a2, voffA);
;             PG8_WAIT_V(8); PG8_WAIT_L(0); PG8_BAR; PG8_MMA(1, 0, At, B0); PG8_MMA(1, 1, At, B1); PG8_BAR; PG8_SCHED;
.LBB0_139:
	ds_read_b128 v[154:157], v150
	ds_read_b128 v[158:161], v150 offset:1024
	ds_read_b128 v[162:165], v150 offset:2048
	ds_read_b128 v[166:169], v150 offset:3072
	ds_read_b128 v[170:173], v151
	ds_read_b128 v[174:177], v151 offset:1024
	ds_read_b128 v[178:181], v151 offset:2048
	ds_read_b128 v[194:197], v151 offset:3072
	s_add_u32 s54, s70, 0x1fc000
	s_addc_u32 s55, s71, 0
	s_cmp_eq_u32 s51, 28
	s_cselect_b32 s78, s6, s54
	s_cselect_b32 s79, s7, s55
	s_cselect_b32 s76, s68, s41
	s_cselect_b32 s77, s69, s49
	s_add_u32 s74, s78, 0x200000
	s_addc_u32 s75, s79, 0
	s_add_i32 m0, s20, 0xc000
	ds_read_b128 v[198:201], v152
	ds_read_b128 v[202:205], v152 offset:1024
	ds_read_b128 v[206:209], v152 offset:2048
	ds_read_b128 v[210:213], v152 offset:3072
	ds_read_b128 v[214:217], v152 offset:4096
	ds_read_b128 v[218:221], v152 offset:5120
	ds_read_b128 v[222:225], v152 offset:6144
	ds_read_b128 v[226:229], v152 offset:7168
	global_load_lds_dwordx4 v138, s[70:71]
	s_add_i32 m0, s20, 0xe000
	s_nop 0
	global_load_lds_dwordx4 v140, s[70:71]
	s_waitcnt vmcnt(8)
	s_waitcnt lgkmcnt(0)
	s_barrier
	s_waitcnt lgkmcnt(0)
	v_mfma_f32_16x16x32_bf16 v[124:127], v[154:157], v[198:201], v[124:127]
	v_mfma_f32_16x16x32_bf16 v[124:127], v[158:161], v[202:205], v[124:127]
	v_mfma_f32_16x16x32_bf16 v[116:119], v[162:165], v[198:201], v[116:119]
	v_mfma_f32_16x16x32_bf16 v[116:119], v[166:169], v[202:205], v[116:119]
	v_mfma_f32_16x16x32_bf16 v[120:123], v[170:173], v[198:201], v[120:123]
	v_mfma_f32_16x16x32_bf16 v[120:123], v[174:177], v[202:205], v[120:123]
	v_mfma_f32_16x16x32_bf16 v[112:115], v[178:181], v[198:201], v[112:115]
	v_mfma_f32_16x16x32_bf16 v[112:115], v[194:197], v[202:205], v[112:115]
	v_mfma_f32_16x16x32_bf16 v[108:111], v[154:157], v[206:209], v[108:111]
	v_mfma_f32_16x16x32_bf16 v[108:111], v[158:161], v[210:213], v[108:111]
	v_mfma_f32_16x16x32_bf16 v[100:103], v[162:165], v[206:209], v[100:103]
	v_mfma_f32_16x16x32_bf16 v[100:103], v[166:169], v[210:213], v[100:103]
	v_mfma_f32_16x16x32_bf16 v[104:107], v[170:173], v[206:209], v[104:107]
	v_mfma_f32_16x16x32_bf16 v[104:107], v[174:177], v[210:213], v[104:107]
	v_mfma_f32_16x16x32_bf16 v[96:99], v[178:181], v[206:209], v[96:99]
	v_mfma_f32_16x16x32_bf16 v[96:99], v[194:197], v[210:213], v[96:99]
	v_mfma_f32_16x16x32_bf16 v[92:95], v[154:157], v[214:217], v[92:95]
	v_mfma_f32_16x16x32_bf16 v[92:95], v[158:161], v[218:221], v[92:95]
	v_mfma_f32_16x16x32_bf16 v[84:87], v[162:165], v[214:217], v[84:87]
	v_mfma_f32_16x16x32_bf16 v[84:87], v[166:169], v[218:221], v[84:87]
	v_mfma_f32_16x16x32_bf16 v[88:91], v[170:173], v[214:217], v[88:91]
	v_mfma_f32_16x16x32_bf16 v[88:91], v[174:177], v[218:221], v[88:91]
	v_mfma_f32_16x16x32_bf16 v[80:83], v[178:181], v[214:217], v[80:83]
	v_mfma_f32_16x16x32_bf16 v[80:83], v[194:197], v[218:221], v[80:83]
	v_mfma_f32_16x16x32_bf16 v[76:79], v[154:157], v[222:225], v[76:79]
	v_mfma_f32_16x16x32_bf16 v[76:79], v[158:161], v[226:229], v[76:79]
	v_mfma_f32_16x16x32_bf16 v[68:71], v[162:165], v[222:225], v[68:71]
	v_mfma_f32_16x16x32_bf16 v[68:71], v[166:169], v[226:229], v[68:71]
	v_mfma_f32_16x16x32_bf16 v[72:75], v[170:173], v[222:225], v[72:75]
	v_mfma_f32_16x16x32_bf16 v[72:75], v[174:177], v[226:229], v[72:75]
	v_mfma_f32_16x16x32_bf16 v[64:67], v[178:181], v[222:225], v[64:67]
	v_mfma_f32_16x16x32_bf16 v[64:67], v[194:197], v[226:229], v[64:67]
	s_barrier
	s_add_i32 s54, s42, s18
	s_mov_b32 m0, s54
	ds_read_b128 v[198:201], v152 offset:16384
	ds_read_b128 v[202:205], v152 offset:17408
	ds_read_b128 v[206:209], v152 offset:18432
	ds_read_b128 v[210:213], v152 offset:19456
	ds_read_b128 v[214:217], v152 offset:20480
	ds_read_b128 v[218:221], v152 offset:21504
	ds_read_b128 v[222:225], v152 offset:22528
	ds_read_b128 v[226:229], v152 offset:23552
	global_load_lds_dwordx4 v132, s[76:77]
	s_add_i32 m0, s54, 0x2000
	s_add_u32 s54, s76, 0x4000
	s_addc_u32 s55, s77, 0
	s_add_i32 s56, s43, s18
	global_load_lds_dwordx4 v128, s[76:77]
	s_mov_b32 m0, s56
	s_nop 0
	global_load_lds_dwordx4 v132, s[54:55]
	s_add_i32 m0, s56, 0x2000
	s_nop 0
	global_load_lds_dwordx4 v128, s[54:55]
	s_mov_b32 m0, s20
	s_nop 0
	global_load_lds_dwordx4 v134, s[78:79]
	s_mov_b32 m0, s21
	s_nop 0
	global_load_lds_dwordx4 v130, s[78:79]
	s_waitcnt vmcnt(8)
	s_waitcnt lgkmcnt(0)
	s_barrier
	s_waitcnt lgkmcnt(0)
	v_mfma_f32_16x16x32_bf16 v[60:63], v[154:157], v[198:201], v[60:63]
	v_mfma_f32_16x16x32_bf16 v[60:63], v[158:161], v[202:205], v[60:63]
	v_mfma_f32_16x16x32_bf16 v[52:55], v[162:165], v[198:201], v[52:55]
	v_mfma_f32_16x16x32_bf16 v[52:55], v[166:169], v[202:205], v[52:55]
	v_mfma_f32_16x16x32_bf16 v[56:59], v[170:173], v[198:201], v[56:59]
	v_mfma_f32_16x16x32_bf16 v[56:59], v[174:177], v[202:205], v[56:59]
	v_mfma_f32_16x16x32_bf16 v[48:51], v[178:181], v[198:201], v[48:51]
	v_mfma_f32_16x16x32_bf16 v[48:51], v[194:197], v[202:205], v[48:51]
	v_mfma_f32_16x16x32_bf16 v[44:47], v[154:157], v[206:209], v[44:47]
	v_mfma_f32_16x16x32_bf16 v[44:47], v[158:161], v[210:213], v[44:47]
	v_mfma_f32_16x16x32_bf16 v[36:39], v[162:165], v[206:209], v[36:39]
	v_mfma_f32_16x16x32_bf16 v[36:39], v[166:169], v[210:213], v[36:39]
	v_mfma_f32_16x16x32_bf16 v[40:43], v[170:173], v[206:209], v[40:43]
	v_mfma_f32_16x16x32_bf16 v[40:43], v[174:177], v[210:213], v[40:43]
	v_mfma_f32_16x16x32_bf16 v[32:35], v[178:181], v[206:209], v[32:35]
	v_mfma_f32_16x16x32_bf16 v[32:35], v[194:197], v[210:213], v[32:35]
	v_mfma_f32_16x16x32_bf16 v[28:31], v[154:157], v[214:217], v[28:31]
	v_mfma_f32_16x16x32_bf16 v[28:31], v[158:161], v[218:221], v[28:31]
	v_mfma_f32_16x16x32_bf16 v[20:23], v[162:165], v[214:217], v[20:23]
	v_mfma_f32_16x16x32_bf16 v[20:23], v[166:169], v[218:221], v[20:23]
	v_mfma_f32_16x16x32_bf16 v[24:27], v[170:173], v[214:217], v[24:27]
	v_mfma_f32_16x16x32_bf16 v[24:27], v[174:177], v[218:221], v[24:27]
	v_mfma_f32_16x16x32_bf16 v[16:19], v[178:181], v[214:217], v[16:19]
	v_mfma_f32_16x16x32_bf16 v[16:19], v[194:197], v[218:221], v[16:19]
	v_mfma_f32_16x16x32_bf16 v[12:15], v[154:157], v[222:225], v[12:15]
	v_mfma_f32_16x16x32_bf16 v[12:15], v[158:161], v[226:229], v[12:15]
	v_mfma_f32_16x16x32_bf16 v[4:7], v[162:165], v[222:225], v[4:7]
	v_mfma_f32_16x16x32_bf16 v[4:7], v[166:169], v[226:229], v[4:7]
	v_mfma_f32_16x16x32_bf16 v[8:11], v[170:173], v[222:225], v[8:11]
	v_mfma_f32_16x16x32_bf16 v[8:11], v[174:177], v[226:229], v[8:11]
	v_mfma_f32_16x16x32_bf16 v[0:3], v[178:181], v[222:225], v[0:3]
	v_mfma_f32_16x16x32_bf16 v[0:3], v[194:197], v[226:229], v[0:3]
	s_barrier
; #define PG8_STAGE(bufoff, gbase, voff) do { _Pragma("unroll") for (int _i = 0; _i < 2; ++_i) \
;         __builtin_amdgcn_global_load_lds((const unsigned*)((const char*)(gbase) + (voff)[_i]), (LAS unsigned*)(lds + (bufoff) + ldsw + _i * 8192), 16, 0, 0); } while (0)
; #define PG8_LDA(dst, b, h) do { _Pragma("unroll") for (int m = 0; m < 4; ++m) _Pragma("unroll") for (int k = 0; k < 2; ++k) dst[m][k] = *(const LAS bf16x8*)(lds + PG8_SA(b, h) + aoff + m * 2048 + k * 1024); } while (0)
; #define PG8_LDB(dst, b, h) do { _Pragma("unroll") for (int n = 0; n < 2; ++n) _Pragma("unroll") for (int k = 0; k < 2; ++k) dst[n][k] = *(const LAS bf16x8*)(lds + PG8_SB(b, h) + boff + n * 2048 + k * 1024); } while (0)
; #define PG8_MMA(ai, bj, At, Bt) do { __builtin_amdgcn_s_setprio(1); _Pragma("unroll") for (int m = 0; m < 4; ++m) _Pragma("unroll") for (int n = 0; n < 2; ++n) _Pragma("unroll") for (int k = 0; k < 2; ++k) \
;         acc[ai][bj][m][n] = __builtin_amdgcn_mfma_f32_16x16x32_bf16(Bt[n][k], At[m][k], acc[ai][bj][m][n], 0, 0, 0); __builtin_amdgcn_s_setprio(0); } while (0)
; #define PG8_WAIT_V(n) asm volatile("s_waitcnt vmcnt(" #n ")" ::: "memory")
; #define PG8_WAIT_L(n) asm volatile("s_waitcnt lgkmcnt(" #n ")" ::: "memory")
; #define PG8_BAR __builtin_amdgcn_s_barrier()
; #define PG8_SCHED __builtin_amdgcn_sched_barrier(0)
; template <bool ALIGN_EPI, class Epi, class Sched>
; __device__ __forceinline__ void gemm_phase(LAS unsigned char* lds, const int lda, const int ldb, const int K, const Sched& S, const Epi& E, const size_t kstepA = (size_t)(BK * 2), const size_t kstepB = (size_t)(BK * 2)) {
;     ...
;             PG8_LDB(B0, 1, 0); PG8_LDB(B1, 1, 1); PG8_SCHED; PG8_LDA(At, 1, 0); PG8_STAGE(PG8_SA(0, 1), a2 + hstepA, voffA);
;             PG8_WAIT_V(8); PG8_WAIT_L(0); PG8_BAR; PG8_MMA(0, 0, At, B0); PG8_MMA(0, 1, At, B1); PG8_BAR; PG8_SCHED;
;             PG8_LDA(At, 1, 1); PG8_STAGE(PG8_SB(1, 0), b3, voffB); PG8_STAGE(PG8_SB(1, 1), b3 + hstepB, voffB); PG8_STAGE(PG8_SA(1, 0), a3, voffA);
;             PG8_WAIT_V(8); PG8_WAIT_L(0); PG8_BAR; PG8_MMA(1, 0, At, B0); PG8_MMA(1, 1, At, B1); PG8_BAR; PG8_SCHED;
;         }
;         if constexpr (ALIGN_EPI) { if (wr == 0) PG8_BAR; }
	s_add_i32 s56, 0, 0x18000
	v_add_u32_e32 v146, s56, v149
	s_add_i32 s57, 0, 0x1c000
	ds_read_b128 v[154:157], v146
	ds_read_b128 v[158:161], v146 offset:1024
	ds_read_b128 v[162:165], v146 offset:2048
	ds_read_b128 v[166:169], v146 offset:3072
	v_add_u32_e32 v146, s57, v149
	ds_read_b128 v[170:173], v146
	ds_read_b128 v[174:177], v146 offset:1024
	ds_read_b128 v[178:181], v146 offset:2048
	ds_read_b128 v[194:197], v146 offset:3072
	s_add_u32 s54, s78, 0x4000
	s_addc_u32 s55, s79, 0
	s_mov_b32 m0, s22
	ds_read_b128 v[198:201], v152 offset:32768
	ds_read_b128 v[202:205], v152 offset:33792
	ds_read_b128 v[206:209], v152 offset:34816
	ds_read_b128 v[210:213], v152 offset:35840
	ds_read_b128 v[214:217], v152 offset:36864
	ds_read_b128 v[218:221], v152 offset:37888
	ds_read_b128 v[222:225], v152 offset:38912
	ds_read_b128 v[226:229], v152 offset:39936
	global_load_lds_dwordx4 v134, s[54:55]
	s_mov_b32 m0, s23
	s_nop 0
	global_load_lds_dwordx4 v130, s[54:55]
	s_waitcnt vmcnt(8)
	s_waitcnt lgkmcnt(0)
	s_barrier
	s_waitcnt lgkmcnt(0)
	v_mfma_f32_16x16x32_bf16 v[124:127], v[154:157], v[198:201], v[124:127]
	v_mfma_f32_16x16x32_bf16 v[124:127], v[158:161], v[202:205], v[124:127]
	v_mfma_f32_16x16x32_bf16 v[116:119], v[162:165], v[198:201], v[116:119]
	v_mfma_f32_16x16x32_bf16 v[116:119], v[166:169], v[202:205], v[116:119]
	v_mfma_f32_16x16x32_bf16 v[120:123], v[170:173], v[198:201], v[120:123]
	v_mfma_f32_16x16x32_bf16 v[120:123], v[174:177], v[202:205], v[120:123]
	v_mfma_f32_16x16x32_bf16 v[112:115], v[178:181], v[198:201], v[112:115]
	v_mfma_f32_16x16x32_bf16 v[112:115], v[194:197], v[202:205], v[112:115]
	v_mfma_f32_16x16x32_bf16 v[108:111], v[154:157], v[206:209], v[108:111]
	v_mfma_f32_16x16x32_bf16 v[108:111], v[158:161], v[210:213], v[108:111]
	v_mfma_f32_16x16x32_bf16 v[100:103], v[162:165], v[206:209], v[100:103]
	v_mfma_f32_16x16x32_bf16 v[100:103], v[166:169], v[210:213], v[100:103]
	v_mfma_f32_16x16x32_bf16 v[104:107], v[170:173], v[206:209], v[104:107]
	v_mfma_f32_16x16x32_bf16 v[104:107], v[174:177], v[210:213], v[104:107]
	v_mfma_f32_16x16x32_bf16 v[96:99], v[178:181], v[206:209], v[96:99]
	v_mfma_f32_16x16x32_bf16 v[96:99], v[194:197], v[210:213], v[96:99]
	v_mfma_f32_16x16x32_bf16 v[92:95], v[154:157], v[214:217], v[92:95]
	v_mfma_f32_16x16x32_bf16 v[92:95], v[158:161], v[218:221], v[92:95]
	v_mfma_f32_16x16x32_bf16 v[84:87], v[162:165], v[214:217], v[84:87]
	v_mfma_f32_16x16x32_bf16 v[84:87], v[166:169], v[218:221], v[84:87]
	v_mfma_f32_16x16x32_bf16 v[88:91], v[170:173], v[214:217], v[88:91]
	v_mfma_f32_16x16x32_bf16 v[88:91], v[174:177], v[218:221], v[88:91]
	v_mfma_f32_16x16x32_bf16 v[80:83], v[178:181], v[214:217], v[80:83]
	v_mfma_f32_16x16x32_bf16 v[80:83], v[194:197], v[218:221], v[80:83]
	v_mfma_f32_16x16x32_bf16 v[76:79], v[154:157], v[222:225], v[76:79]
	v_mfma_f32_16x16x32_bf16 v[76:79], v[158:161], v[226:229], v[76:79]
	v_mfma_f32_16x16x32_bf16 v[68:71], v[162:165], v[222:225], v[68:71]
	v_mfma_f32_16x16x32_bf16 v[68:71], v[166:169], v[226:229], v[68:71]
	v_mfma_f32_16x16x32_bf16 v[72:75], v[170:173], v[222:225], v[72:75]
	v_mfma_f32_16x16x32_bf16 v[72:75], v[174:177], v[226:229], v[72:75]
	v_mfma_f32_16x16x32_bf16 v[64:67], v[178:181], v[222:225], v[64:67]
	v_mfma_f32_16x16x32_bf16 v[64:67], v[194:197], v[226:229], v[64:67]
	s_barrier
	s_add_u32 s54, s76, 0x160000
	s_addc_u32 s55, s77, 0
	s_add_i32 s56, s56, s18
	s_mov_b32 m0, s56
	ds_read_b128 v[198:201], v152 offset:49152
	ds_read_b128 v[202:205], v152 offset:50176
	ds_read_b128 v[206:209], v152 offset:51200
	ds_read_b128 v[210:213], v152 offset:52224
	ds_read_b128 v[214:217], v152 offset:53248
	ds_read_b128 v[218:221], v152 offset:54272
	ds_read_b128 v[222:225], v152 offset:55296
	ds_read_b128 v[226:229], v152 offset:56320
	global_load_lds_dwordx4 v132, s[54:55]
	s_add_i32 m0, s56, 0x2000
	s_nop 0
	global_load_lds_dwordx4 v128, s[54:55]
	s_add_u32 s54, s76, 0x164000
	s_addc_u32 s55, s77, 0
	s_add_i32 s56, s57, s18
	s_mov_b32 m0, s56
	s_nop 0
	global_load_lds_dwordx4 v132, s[54:55]
	s_add_i32 m0, s56, 0x2000
	s_nop 0
	global_load_lds_dwordx4 v128, s[54:55]
	s_mov_b32 m0, s31
	s_nop 0
	global_load_lds_dwordx4 v134, s[74:75]
	s_mov_b32 m0, s33
	s_nop 0
	global_load_lds_dwordx4 v130, s[74:75]
	s_waitcnt vmcnt(8)
	s_waitcnt lgkmcnt(0)
	s_barrier
	s_waitcnt lgkmcnt(0)
	v_mfma_f32_16x16x32_bf16 v[60:63], v[154:157], v[198:201], v[60:63]
	v_mfma_f32_16x16x32_bf16 v[60:63], v[158:161], v[202:205], v[60:63]
	v_mfma_f32_16x16x32_bf16 v[52:55], v[162:165], v[198:201], v[52:55]
	v_mfma_f32_16x16x32_bf16 v[52:55], v[166:169], v[202:205], v[52:55]
	v_mfma_f32_16x16x32_bf16 v[56:59], v[170:173], v[198:201], v[56:59]
	v_mfma_f32_16x16x32_bf16 v[56:59], v[174:177], v[202:205], v[56:59]
	v_mfma_f32_16x16x32_bf16 v[48:51], v[178:181], v[198:201], v[48:51]
	v_mfma_f32_16x16x32_bf16 v[48:51], v[194:197], v[202:205], v[48:51]
	v_mfma_f32_16x16x32_bf16 v[44:47], v[154:157], v[206:209], v[44:47]
	v_mfma_f32_16x16x32_bf16 v[44:47], v[158:161], v[210:213], v[44:47]
	v_mfma_f32_16x16x32_bf16 v[36:39], v[162:165], v[206:209], v[36:39]
	v_mfma_f32_16x16x32_bf16 v[36:39], v[166:169], v[210:213], v[36:39]
	v_mfma_f32_16x16x32_bf16 v[40:43], v[170:173], v[206:209], v[40:43]
	v_mfma_f32_16x16x32_bf16 v[40:43], v[174:177], v[210:213], v[40:43]
	v_mfma_f32_16x16x32_bf16 v[32:35], v[178:181], v[206:209], v[32:35]
	v_mfma_f32_16x16x32_bf16 v[32:35], v[194:197], v[210:213], v[32:35]
	v_mfma_f32_16x16x32_bf16 v[28:31], v[154:157], v[214:217], v[28:31]
	v_mfma_f32_16x16x32_bf16 v[28:31], v[158:161], v[218:221], v[28:31]
	v_mfma_f32_16x16x32_bf16 v[20:23], v[162:165], v[214:217], v[20:23]
	v_mfma_f32_16x16x32_bf16 v[20:23], v[166:169], v[218:221], v[20:23]
	v_mfma_f32_16x16x32_bf16 v[24:27], v[170:173], v[214:217], v[24:27]
	v_mfma_f32_16x16x32_bf16 v[24:27], v[174:177], v[218:221], v[24:27]
	v_mfma_f32_16x16x32_bf16 v[16:19], v[178:181], v[214:217], v[16:19]
	v_mfma_f32_16x16x32_bf16 v[16:19], v[194:197], v[218:221], v[16:19]
	v_mfma_f32_16x16x32_bf16 v[12:15], v[154:157], v[222:225], v[12:15]
	v_mfma_f32_16x16x32_bf16 v[12:15], v[158:161], v[226:229], v[12:15]
	v_mfma_f32_16x16x32_bf16 v[4:7], v[162:165], v[222:225], v[4:7]
	v_mfma_f32_16x16x32_bf16 v[4:7], v[166:169], v[226:229], v[4:7]
	v_mfma_f32_16x16x32_bf16 v[8:11], v[170:173], v[222:225], v[8:11]
	v_mfma_f32_16x16x32_bf16 v[8:11], v[174:177], v[226:229], v[8:11]
	v_mfma_f32_16x16x32_bf16 v[0:3], v[178:181], v[222:225], v[0:3]
	v_mfma_f32_16x16x32_bf16 v[0:3], v[194:197], v[226:229], v[0:3]
	s_barrier
	s_add_i32 s51, s51, 2
	s_add_u32 s41, s41, 0x2c0000
	s_addc_u32 s49, s49, 0
	s_add_u32 s70, s70, 0x400000
	s_addc_u32 s71, s71, 0
	s_cmp_gt_u32 s51, 29
	s_cbranch_scc0 .LBB0_139
	s_and_b64 vcc, exec, s[12:13]
	s_cbranch_vccz .LBB0_142
	s_barrier

; #define PG8_STAGE(bufoff, gbase, voff) do { _Pragma("unroll") for (int _i = 0; _i < 2; ++_i) \
;         __builtin_amdgcn_global_load_lds((const unsigned*)((const char*)(gbase) + (voff)[_i]), (LAS unsigned*)(lds + (bufoff) + ldsw + _i * 8192), 16, 0, 0); } while (0)
; #define PG8_LDA(dst, b, h) do { _Pragma("unroll") for (int m = 0; m < 4; ++m) _Pragma("unroll") for (int k = 0; k < 2; ++k) dst[m][k] = *(const LAS bf16x8*)(lds + PG8_SA(b, h) + aoff + m * 2048 + k * 1024); } while (0)
; #define PG8_LDB(dst, b, h) do { _Pragma("unroll") for (int n = 0; n < 2; ++n) _Pragma("unroll") for (int k = 0; k < 2; ++k) dst[n][k] = *(const LAS bf16x8*)(lds + PG8_SB(b, h) + boff + n * 2048 + k * 1024); } while (0)
; #define PG8_MMA(ai, bj, At, Bt) do { __builtin_amdgcn_s_setprio(1); _Pragma("unroll") for (int m = 0; m < 4; ++m) _Pragma("unroll") for (int n = 0; n < 2; ++n) _Pragma("unroll") for (int k = 0; k < 2; ++k) \
;         acc[ai][bj][m][n] = __builtin_amdgcn_mfma_f32_16x16x32_bf16(Bt[n][k], At[m][k], acc[ai][bj][m][n], 0, 0, 0); __builtin_amdgcn_s_setprio(0); } while (0)
; #define PG8_WAIT_V(n) asm volatile("s_waitcnt vmcnt(" #n ")" ::: "memory")
; #define PG8_WAIT_L(n) asm volatile("s_waitcnt lgkmcnt(" #n ")" ::: "memory")
; template <bool ALIGN_EPI, class Epi, class Sched>
; __device__ __forceinline__ void gemm_phase(LAS unsigned char* lds, const int lda, const int ldb, const int K, const Sched& S, const Epi& E, const size_t kstepA = (size_t)(BK * 2), const size_t kstepB = (size_t)(BK * 2)) {
;     ...
;         for (int t = 0; t < nt; t += 2) {
;             const bool last = (t == nt - 2);
;             const char* a1 = cA + (size_t)(t + 1) * kstepA;
;             const char* a2 = last ? nA : cA + (size_t)(t + 2) * kstepA; const char* b2 = last ? nB : cB + (size_t)(t + 2) * kstep;
;             const char* a3 = a2 + kstepA; const char* b3 = b2 + kstep;
;             PG8_LDB(B0, 0, 0); PG8_LDB(B1, 0, 1); PG8_SCHED; PG8_LDA(At, 0, 0); PG8_STAGE(PG8_SA(1, 1), a1 + hstepA, voffA);
;             PG8_WAIT_V(8); PG8_WAIT_L(0); PG8_BAR; PG8_MMA(0, 0, At, B0); PG8_MMA(0, 1, At, B1); PG8_BAR; PG8_SCHED;
;             PG8_LDA(At, 0, 1); PG8_STAGE(PG8_SB(0, 0), b2, voffB); PG8_STAGE(PG8_SB(0, 1), b2 + hstepB, voffB); PG8_STAGE(PG8_SA(0, 0), a2, voffA);
;             PG8_WAIT_V(8); PG8_WAIT_L(0); PG8_BAR; PG8_MMA(1, 0, At, B0); PG8_MMA(1, 1, At, B1); PG8_BAR; PG8_SCHED;
.LBB0_218:
	ds_read_b128 v[64:67], v193
	ds_read_b128 v[68:71], v193 offset:1024
	ds_read_b128 v[80:83], v193 offset:2048
	ds_read_b128 v[84:87], v193 offset:3072
	ds_read_b128 v[144:147], v232
	ds_read_b128 v[148:151], v232 offset:1024
	ds_read_b128 v[152:155], v232 offset:2048
	ds_read_b128 v[156:159], v232 offset:3072
	s_add_u32 s54, s82, 0x1fc000
	s_addc_u32 s55, s83, 0
	s_cmpk_eq_i32 s51, 0x54
	s_cselect_b32 vcc_lo, s6, s54
	s_cselect_b32 vcc_hi, s7, s55
	s_cselect_b32 s96, s78, s13
	s_cselect_b32 s97, s79, s50
	s_add_u32 s94, vcc_lo, 0x200000
	s_addc_u32 s95, vcc_hi, 0
	s_add_i32 m0, s19, 0xc000
	ds_read_b128 v[160:163], v233
	ds_read_b128 v[164:167], v233 offset:1024
	ds_read_b128 v[168:171], v233 offset:2048
	ds_read_b128 v[172:175], v233 offset:3072
	ds_read_b128 v[176:179], v233 offset:4096
	ds_read_b128 v[180:183], v233 offset:5120
	ds_read_b128 v[212:215], v233 offset:6144
	ds_read_b128 v[216:219], v233 offset:7168
	global_load_lds_dwordx4 v204, s[82:83]
	s_add_i32 m0, s19, 0xe000
	s_nop 0
	global_load_lds_dwordx4 v206, s[82:83]
	s_waitcnt vmcnt(8)
	s_waitcnt lgkmcnt(0)
	s_barrier
	s_waitcnt lgkmcnt(0)
	v_mfma_f32_16x16x32_bf16 v[140:143], v[64:67], v[160:163], v[140:143]
	v_mfma_f32_16x16x32_bf16 v[140:143], v[68:71], v[164:167], v[140:143]
	v_mfma_f32_16x16x32_bf16 v[136:139], v[80:83], v[160:163], v[136:139]
	v_mfma_f32_16x16x32_bf16 v[136:139], v[84:87], v[164:167], v[136:139]
	v_mfma_f32_16x16x32_bf16 v[132:135], v[144:147], v[160:163], v[132:135]
	v_mfma_f32_16x16x32_bf16 v[132:135], v[148:151], v[164:167], v[132:135]
	v_mfma_f32_16x16x32_bf16 v[128:131], v[152:155], v[160:163], v[128:131]
	v_mfma_f32_16x16x32_bf16 v[128:131], v[156:159], v[164:167], v[128:131]
	v_mfma_f32_16x16x32_bf16 v[124:127], v[64:67], v[168:171], v[124:127]
	v_mfma_f32_16x16x32_bf16 v[124:127], v[68:71], v[172:175], v[124:127]
	v_mfma_f32_16x16x32_bf16 v[120:123], v[80:83], v[168:171], v[120:123]
	v_mfma_f32_16x16x32_bf16 v[120:123], v[84:87], v[172:175], v[120:123]
	v_mfma_f32_16x16x32_bf16 v[116:119], v[144:147], v[168:171], v[116:119]
	v_mfma_f32_16x16x32_bf16 v[116:119], v[148:151], v[172:175], v[116:119]
	v_mfma_f32_16x16x32_bf16 v[112:115], v[152:155], v[168:171], v[112:115]
	v_mfma_f32_16x16x32_bf16 v[112:115], v[156:159], v[172:175], v[112:115]
	v_mfma_f32_16x16x32_bf16 v[108:111], v[64:67], v[176:179], v[108:111]
	v_mfma_f32_16x16x32_bf16 v[108:111], v[68:71], v[180:183], v[108:111]
	v_mfma_f32_16x16x32_bf16 v[104:107], v[80:83], v[176:179], v[104:107]
	v_mfma_f32_16x16x32_bf16 v[104:107], v[84:87], v[180:183], v[104:107]
	v_mfma_f32_16x16x32_bf16 v[100:103], v[144:147], v[176:179], v[100:103]
	v_mfma_f32_16x16x32_bf16 v[100:103], v[148:151], v[180:183], v[100:103]
	v_mfma_f32_16x16x32_bf16 v[96:99], v[152:155], v[176:179], v[96:99]
	v_mfma_f32_16x16x32_bf16 v[96:99], v[156:159], v[180:183], v[96:99]
	v_mfma_f32_16x16x32_bf16 v[92:95], v[64:67], v[212:215], v[92:95]
	v_mfma_f32_16x16x32_bf16 v[92:95], v[68:71], v[216:219], v[92:95]
	v_mfma_f32_16x16x32_bf16 v[88:91], v[80:83], v[212:215], v[88:91]
	v_mfma_f32_16x16x32_bf16 v[88:91], v[84:87], v[216:219], v[88:91]
	v_mfma_f32_16x16x32_bf16 v[76:79], v[144:147], v[212:215], v[76:79]
	v_mfma_f32_16x16x32_bf16 v[76:79], v[148:151], v[216:219], v[76:79]
	v_mfma_f32_16x16x32_bf16 v[72:75], v[152:155], v[212:215], v[72:75]
	v_mfma_f32_16x16x32_bf16 v[72:75], v[156:159], v[216:219], v[72:75]
	s_barrier
	s_add_i32 s54, s33, s18
	s_mov_b32 m0, s54
	ds_read_b128 v[160:163], v233 offset:16384
	ds_read_b128 v[164:167], v233 offset:17408
	ds_read_b128 v[168:171], v233 offset:18432
	ds_read_b128 v[172:175], v233 offset:19456
	ds_read_b128 v[176:179], v233 offset:20480
	ds_read_b128 v[180:183], v233 offset:21504
	ds_read_b128 v[212:215], v233 offset:22528
	ds_read_b128 v[216:219], v233 offset:23552
	global_load_lds_dwordx4 v196, s[96:97]
	s_add_i32 m0, s54, 0x2000
	s_add_u32 s54, s96, 0x4000
	s_addc_u32 s55, s97, 0
	s_add_i32 s56, s42, s18
	global_load_lds_dwordx4 v200, s[96:97]
	s_mov_b32 m0, s56
	s_nop 0
	global_load_lds_dwordx4 v196, s[54:55]
	s_add_i32 m0, s56, 0x2000
	s_nop 0
	global_load_lds_dwordx4 v200, s[54:55]
	v_lshl_add_u64 v[220:221], vcc, 0, v[194:195]
	s_mov_b32 m0, s19
	s_nop 0
	global_load_lds_dwordx4 v[220:221], off
	v_lshl_add_u64 v[220:221], vcc, 0, v[198:199]
	s_mov_b32 m0, s20
	s_nop 0
	global_load_lds_dwordx4 v[220:221], off
	s_waitcnt vmcnt(8)
	s_waitcnt lgkmcnt(0)
	s_barrier
	s_waitcnt lgkmcnt(0)
	v_mfma_f32_16x16x32_bf16 v[60:63], v[64:67], v[160:163], v[60:63]
	v_mfma_f32_16x16x32_bf16 v[60:63], v[68:71], v[164:167], v[60:63]
	v_mfma_f32_16x16x32_bf16 v[56:59], v[80:83], v[160:163], v[56:59]
	v_mfma_f32_16x16x32_bf16 v[56:59], v[84:87], v[164:167], v[56:59]
	v_mfma_f32_16x16x32_bf16 v[52:55], v[144:147], v[160:163], v[52:55]
	v_mfma_f32_16x16x32_bf16 v[52:55], v[148:151], v[164:167], v[52:55]
	v_mfma_f32_16x16x32_bf16 v[48:51], v[152:155], v[160:163], v[48:51]
	v_mfma_f32_16x16x32_bf16 v[48:51], v[156:159], v[164:167], v[48:51]
	v_mfma_f32_16x16x32_bf16 v[44:47], v[64:67], v[168:171], v[44:47]
	v_mfma_f32_16x16x32_bf16 v[44:47], v[68:71], v[172:175], v[44:47]
	v_mfma_f32_16x16x32_bf16 v[40:43], v[80:83], v[168:171], v[40:43]
	v_mfma_f32_16x16x32_bf16 v[40:43], v[84:87], v[172:175], v[40:43]
	v_mfma_f32_16x16x32_bf16 v[36:39], v[144:147], v[168:171], v[36:39]
	v_mfma_f32_16x16x32_bf16 v[36:39], v[148:151], v[172:175], v[36:39]
	v_mfma_f32_16x16x32_bf16 v[32:35], v[152:155], v[168:171], v[32:35]
	v_mfma_f32_16x16x32_bf16 v[32:35], v[156:159], v[172:175], v[32:35]
	v_mfma_f32_16x16x32_bf16 v[28:31], v[64:67], v[176:179], v[28:31]
	v_mfma_f32_16x16x32_bf16 v[28:31], v[68:71], v[180:183], v[28:31]
	v_mfma_f32_16x16x32_bf16 v[24:27], v[80:83], v[176:179], v[24:27]
	v_mfma_f32_16x16x32_bf16 v[24:27], v[84:87], v[180:183], v[24:27]
	v_mfma_f32_16x16x32_bf16 v[20:23], v[144:147], v[176:179], v[20:23]
	v_mfma_f32_16x16x32_bf16 v[20:23], v[148:151], v[180:183], v[20:23]
	v_mfma_f32_16x16x32_bf16 v[16:19], v[152:155], v[176:179], v[16:19]
	v_mfma_f32_16x16x32_bf16 v[16:19], v[156:159], v[180:183], v[16:19]
	v_mfma_f32_16x16x32_bf16 v[12:15], v[64:67], v[212:215], v[12:15]
	v_mfma_f32_16x16x32_bf16 v[12:15], v[68:71], v[216:219], v[12:15]
	v_mfma_f32_16x16x32_bf16 v[8:11], v[80:83], v[212:215], v[8:11]
	v_mfma_f32_16x16x32_bf16 v[8:11], v[84:87], v[216:219], v[8:11]
	v_mfma_f32_16x16x32_bf16 v[4:7], v[144:147], v[212:215], v[4:7]
	v_mfma_f32_16x16x32_bf16 v[4:7], v[148:151], v[216:219], v[4:7]
	v_mfma_f32_16x16x32_bf16 v[0:3], v[152:155], v[212:215], v[0:3]
	v_mfma_f32_16x16x32_bf16 v[0:3], v[156:159], v[216:219], v[0:3]
	s_barrier
; #define PG8_STAGE(bufoff, gbase, voff) do { _Pragma("unroll") for (int _i = 0; _i < 2; ++_i) \
;         __builtin_amdgcn_global_load_lds((const unsigned*)((const char*)(gbase) + (voff)[_i]), (LAS unsigned*)(lds + (bufoff) + ldsw + _i * 8192), 16, 0, 0); } while (0)
; #define PG8_LDA(dst, b, h) do { _Pragma("unroll") for (int m = 0; m < 4; ++m) _Pragma("unroll") for (int k = 0; k < 2; ++k) dst[m][k] = *(const LAS bf16x8*)(lds + PG8_SA(b, h) + aoff + m * 2048 + k * 1024); } while (0)
; #define PG8_LDB(dst, b, h) do { _Pragma("unroll") for (int n = 0; n < 2; ++n) _Pragma("unroll") for (int k = 0; k < 2; ++k) dst[n][k] = *(const LAS bf16x8*)(lds + PG8_SB(b, h) + boff + n * 2048 + k * 1024); } while (0)
; #define PG8_MMA(ai, bj, At, Bt) do { __builtin_amdgcn_s_setprio(1); _Pragma("unroll") for (int m = 0; m < 4; ++m) _Pragma("unroll") for (int n = 0; n < 2; ++n) _Pragma("unroll") for (int k = 0; k < 2; ++k) \
;         acc[ai][bj][m][n] = __builtin_amdgcn_mfma_f32_16x16x32_bf16(Bt[n][k], At[m][k], acc[ai][bj][m][n], 0, 0, 0); __builtin_amdgcn_s_setprio(0); } while (0)
; #define PG8_WAIT_V(n) asm volatile("s_waitcnt vmcnt(" #n ")" ::: "memory")
; #define PG8_WAIT_L(n) asm volatile("s_waitcnt lgkmcnt(" #n ")" ::: "memory")
; #define PG8_BAR __builtin_amdgcn_s_barrier()
; #define PG8_SCHED __builtin_amdgcn_sched_barrier(0)
; template <bool ALIGN_EPI, class Epi, class Sched>
; __device__ __forceinline__ void gemm_phase(LAS unsigned char* lds, const int lda, const int ldb, const int K, const Sched& S, const Epi& E, const size_t kstepA = (size_t)(BK * 2), const size_t kstepB = (size_t)(BK * 2)) {
;     ...
;             PG8_LDB(B0, 1, 0); PG8_LDB(B1, 1, 1); PG8_SCHED; PG8_LDA(At, 1, 0); PG8_STAGE(PG8_SA(0, 1), a2 + hstepA, voffA);
;             PG8_WAIT_V(8); PG8_WAIT_L(0); PG8_BAR; PG8_MMA(0, 0, At, B0); PG8_MMA(0, 1, At, B1); PG8_BAR; PG8_SCHED;
;             PG8_LDA(At, 1, 1); PG8_STAGE(PG8_SB(1, 0), b3, voffB); PG8_STAGE(PG8_SB(1, 1), b3 + hstepB, voffB); PG8_STAGE(PG8_SA(1, 0), a3, voffA);
;             PG8_WAIT_V(8); PG8_WAIT_L(0); PG8_BAR; PG8_MMA(1, 0, At, B0); PG8_MMA(1, 1, At, B1); PG8_BAR; PG8_SCHED;
;         }
;         if constexpr (ALIGN_EPI) { if (wr == 0) PG8_BAR; }
	s_add_i32 s56, 0, 0x18000
	s_add_i32 s57, 0, 0x1c000
	v_add_u32_e32 v84, s56, v191
	v_add_u32_e32 v156, s57, v191
	ds_read_b128 v[64:67], v84
	ds_read_b128 v[68:71], v84 offset:1024
	ds_read_b128 v[80:83], v84 offset:2048
	ds_read_b128 v[84:87], v84 offset:3072
	ds_read_b128 v[144:147], v156
	ds_read_b128 v[148:151], v156 offset:1024
	ds_read_b128 v[152:155], v156 offset:2048
	ds_read_b128 v[156:159], v156 offset:3072
	s_add_u32 s54, vcc_lo, 0x4000
	s_addc_u32 s55, vcc_hi, 0
	s_mov_b32 m0, s21
	ds_read_b128 v[160:163], v233 offset:32768
	ds_read_b128 v[164:167], v233 offset:33792
	ds_read_b128 v[168:171], v233 offset:34816
	ds_read_b128 v[172:175], v233 offset:35840
	ds_read_b128 v[176:179], v233 offset:36864
	ds_read_b128 v[180:183], v233 offset:37888
	ds_read_b128 v[212:215], v233 offset:38912
	ds_read_b128 v[216:219], v233 offset:39936
	global_load_lds_dwordx4 v194, s[54:55]
	s_mov_b32 m0, s22
	s_nop 0
	global_load_lds_dwordx4 v198, s[54:55]
	s_waitcnt vmcnt(8)
	s_waitcnt lgkmcnt(0)
	s_barrier
	s_waitcnt lgkmcnt(0)
	v_mfma_f32_16x16x32_bf16 v[140:143], v[64:67], v[160:163], v[140:143]
	v_mfma_f32_16x16x32_bf16 v[140:143], v[68:71], v[164:167], v[140:143]
	v_mfma_f32_16x16x32_bf16 v[136:139], v[80:83], v[160:163], v[136:139]
	v_mfma_f32_16x16x32_bf16 v[136:139], v[84:87], v[164:167], v[136:139]
	v_mfma_f32_16x16x32_bf16 v[132:135], v[144:147], v[160:163], v[132:135]
	v_mfma_f32_16x16x32_bf16 v[132:135], v[148:151], v[164:167], v[132:135]
	v_mfma_f32_16x16x32_bf16 v[128:131], v[152:155], v[160:163], v[128:131]
	v_mfma_f32_16x16x32_bf16 v[128:131], v[156:159], v[164:167], v[128:131]
	v_mfma_f32_16x16x32_bf16 v[124:127], v[64:67], v[168:171], v[124:127]
	v_mfma_f32_16x16x32_bf16 v[124:127], v[68:71], v[172:175], v[124:127]
	v_mfma_f32_16x16x32_bf16 v[120:123], v[80:83], v[168:171], v[120:123]
	v_mfma_f32_16x16x32_bf16 v[120:123], v[84:87], v[172:175], v[120:123]
	v_mfma_f32_16x16x32_bf16 v[116:119], v[144:147], v[168:171], v[116:119]
	v_mfma_f32_16x16x32_bf16 v[116:119], v[148:151], v[172:175], v[116:119]
	v_mfma_f32_16x16x32_bf16 v[112:115], v[152:155], v[168:171], v[112:115]
	v_mfma_f32_16x16x32_bf16 v[112:115], v[156:159], v[172:175], v[112:115]
	v_mfma_f32_16x16x32_bf16 v[108:111], v[64:67], v[176:179], v[108:111]
	v_mfma_f32_16x16x32_bf16 v[108:111], v[68:71], v[180:183], v[108:111]
	v_mfma_f32_16x16x32_bf16 v[104:107], v[80:83], v[176:179], v[104:107]
	v_mfma_f32_16x16x32_bf16 v[104:107], v[84:87], v[180:183], v[104:107]
	v_mfma_f32_16x16x32_bf16 v[100:103], v[144:147], v[176:179], v[100:103]
	v_mfma_f32_16x16x32_bf16 v[100:103], v[148:151], v[180:183], v[100:103]
	v_mfma_f32_16x16x32_bf16 v[96:99], v[152:155], v[176:179], v[96:99]
	v_mfma_f32_16x16x32_bf16 v[96:99], v[156:159], v[180:183], v[96:99]
	v_mfma_f32_16x16x32_bf16 v[92:95], v[64:67], v[212:215], v[92:95]
	v_mfma_f32_16x16x32_bf16 v[92:95], v[68:71], v[216:219], v[92:95]
	v_mfma_f32_16x16x32_bf16 v[88:91], v[80:83], v[212:215], v[88:91]
	v_mfma_f32_16x16x32_bf16 v[88:91], v[84:87], v[216:219], v[88:91]
	v_mfma_f32_16x16x32_bf16 v[76:79], v[144:147], v[212:215], v[76:79]
	v_mfma_f32_16x16x32_bf16 v[76:79], v[148:151], v[216:219], v[76:79]
	v_mfma_f32_16x16x32_bf16 v[72:75], v[152:155], v[212:215], v[72:75]
	v_mfma_f32_16x16x32_bf16 v[72:75], v[156:159], v[216:219], v[72:75]
	s_barrier
	s_add_u32 s54, s96, 0x40000
	s_addc_u32 s55, s97, 0
	s_add_i32 s56, s56, s18
	s_mov_b32 m0, s56
	ds_read_b128 v[160:163], v233 offset:49152
	ds_read_b128 v[164:167], v233 offset:50176
	ds_read_b128 v[168:171], v233 offset:51200
	ds_read_b128 v[172:175], v233 offset:52224
	ds_read_b128 v[176:179], v233 offset:53248
	ds_read_b128 v[180:183], v233 offset:54272
	ds_read_b128 v[212:215], v233 offset:55296
	ds_read_b128 v[216:219], v233 offset:56320
	global_load_lds_dwordx4 v196, s[54:55]
	s_add_i32 m0, s56, 0x2000
	s_nop 0
	global_load_lds_dwordx4 v200, s[54:55]
	s_add_u32 s54, s96, 0x44000
	s_addc_u32 s55, s97, 0
	s_add_i32 s56, s57, s18
	s_mov_b32 m0, s56
	s_nop 0
	global_load_lds_dwordx4 v196, s[54:55]
	s_add_i32 m0, s56, 0x2000
	s_nop 0
	global_load_lds_dwordx4 v200, s[54:55]
	s_mov_b32 m0, s30
	s_nop 0
	global_load_lds_dwordx4 v194, s[94:95]
	s_mov_b32 m0, s31
	s_nop 0
	global_load_lds_dwordx4 v198, s[94:95]
	s_waitcnt vmcnt(8)
	s_waitcnt lgkmcnt(0)
	s_barrier
	s_waitcnt lgkmcnt(0)
	v_mfma_f32_16x16x32_bf16 v[60:63], v[64:67], v[160:163], v[60:63]
	v_mfma_f32_16x16x32_bf16 v[60:63], v[68:71], v[164:167], v[60:63]
	v_mfma_f32_16x16x32_bf16 v[56:59], v[80:83], v[160:163], v[56:59]
	v_mfma_f32_16x16x32_bf16 v[56:59], v[84:87], v[164:167], v[56:59]
	v_mfma_f32_16x16x32_bf16 v[52:55], v[144:147], v[160:163], v[52:55]
	v_mfma_f32_16x16x32_bf16 v[52:55], v[148:151], v[164:167], v[52:55]
	v_mfma_f32_16x16x32_bf16 v[48:51], v[152:155], v[160:163], v[48:51]
	v_mfma_f32_16x16x32_bf16 v[48:51], v[156:159], v[164:167], v[48:51]
	v_mfma_f32_16x16x32_bf16 v[44:47], v[64:67], v[168:171], v[44:47]
	v_mfma_f32_16x16x32_bf16 v[44:47], v[68:71], v[172:175], v[44:47]
	v_mfma_f32_16x16x32_bf16 v[40:43], v[80:83], v[168:171], v[40:43]
	v_mfma_f32_16x16x32_bf16 v[40:43], v[84:87], v[172:175], v[40:43]
	v_mfma_f32_16x16x32_bf16 v[36:39], v[144:147], v[168:171], v[36:39]
	v_mfma_f32_16x16x32_bf16 v[36:39], v[148:151], v[172:175], v[36:39]
	v_mfma_f32_16x16x32_bf16 v[32:35], v[152:155], v[168:171], v[32:35]
	v_mfma_f32_16x16x32_bf16 v[32:35], v[156:159], v[172:175], v[32:35]
	v_mfma_f32_16x16x32_bf16 v[28:31], v[64:67], v[176:179], v[28:31]
	v_mfma_f32_16x16x32_bf16 v[28:31], v[68:71], v[180:183], v[28:31]
	v_mfma_f32_16x16x32_bf16 v[24:27], v[80:83], v[176:179], v[24:27]
	v_mfma_f32_16x16x32_bf16 v[24:27], v[84:87], v[180:183], v[24:27]
	v_mfma_f32_16x16x32_bf16 v[20:23], v[144:147], v[176:179], v[20:23]
	v_mfma_f32_16x16x32_bf16 v[20:23], v[148:151], v[180:183], v[20:23]
	v_mfma_f32_16x16x32_bf16 v[16:19], v[152:155], v[176:179], v[16:19]
	v_mfma_f32_16x16x32_bf16 v[16:19], v[156:159], v[180:183], v[16:19]
	v_mfma_f32_16x16x32_bf16 v[12:15], v[64:67], v[212:215], v[12:15]
	v_mfma_f32_16x16x32_bf16 v[12:15], v[68:71], v[216:219], v[12:15]
	v_mfma_f32_16x16x32_bf16 v[8:11], v[80:83], v[212:215], v[8:11]
	v_mfma_f32_16x16x32_bf16 v[8:11], v[84:87], v[216:219], v[8:11]
	v_mfma_f32_16x16x32_bf16 v[4:7], v[144:147], v[212:215], v[4:7]
	v_mfma_f32_16x16x32_bf16 v[4:7], v[148:151], v[216:219], v[4:7]
	v_mfma_f32_16x16x32_bf16 v[0:3], v[152:155], v[212:215], v[0:3]
	v_mfma_f32_16x16x32_bf16 v[0:3], v[156:159], v[216:219], v[0:3]
	s_barrier
	s_add_i32 s51, s51, 2
	s_add_u32 s13, s13, 0x80000
	s_addc_u32 s50, s50, 0
	s_add_u32 s82, s82, 0x400000
	s_addc_u32 s83, s83, 0
	s_cmpk_gt_u32 s51, 0x55
	s_cbranch_scc0 .LBB0_218
	s_and_b64 vcc, exec, s[84:85]
	s_cbranch_vccz .LBB0_221
	s_barrier

; #define PG8_STAGE(bufoff, gbase, voff) do { _Pragma("unroll") for (int _i = 0; _i < 2; ++_i) \
;         __builtin_amdgcn_global_load_lds((const unsigned*)((const char*)(gbase) + (voff)[_i]), (LAS unsigned*)(lds + (bufoff) + ldsw + _i * 8192), 16, 0, 0); } while (0)
; #define PG8_LDA(dst, b, h) do { _Pragma("unroll") for (int m = 0; m < 4; ++m) _Pragma("unroll") for (int k = 0; k < 2; ++k) dst[m][k] = *(const LAS bf16x8*)(lds + PG8_SA(b, h) + aoff + m * 2048 + k * 1024); } while (0)
; #define PG8_LDB(dst, b, h) do { _Pragma("unroll") for (int n = 0; n < 2; ++n) _Pragma("unroll") for (int k = 0; k < 2; ++k) dst[n][k] = *(const LAS bf16x8*)(lds + PG8_SB(b, h) + boff + n * 2048 + k * 1024); } while (0)
; #define PG8_MMA(ai, bj, At, Bt) do { __builtin_amdgcn_s_setprio(1); _Pragma("unroll") for (int m = 0; m < 4; ++m) _Pragma("unroll") for (int n = 0; n < 2; ++n) _Pragma("unroll") for (int k = 0; k < 2; ++k) \
;         acc[ai][bj][m][n] = __builtin_amdgcn_mfma_f32_16x16x32_bf16(Bt[n][k], At[m][k], acc[ai][bj][m][n], 0, 0, 0); __builtin_amdgcn_s_setprio(0); } while (0)
; #define PG8_WAIT_V(n) asm volatile("s_waitcnt vmcnt(" #n ")" ::: "memory")
; #define PG8_WAIT_L(n) asm volatile("s_waitcnt lgkmcnt(" #n ")" ::: "memory")
; template <bool ALIGN_EPI, class Epi, class Sched>
; __device__ __forceinline__ void gemm_phase(LAS unsigned char* lds, const int lda, const int ldb, const int K, const Sched& S, const Epi& E, const size_t kstepA = (size_t)(BK * 2), const size_t kstepB = (size_t)(BK * 2)) {
;     ...
;         for (int t = 0; t < nt; t += 2) {
;             const bool last = (t == nt - 2);
;             const char* a1 = cA + (size_t)(t + 1) * kstepA;
;             const char* a2 = last ? nA : cA + (size_t)(t + 2) * kstepA; const char* b2 = last ? nB : cB + (size_t)(t + 2) * kstep;
;             const char* a3 = a2 + kstepA; const char* b3 = b2 + kstep;
;             PG8_LDB(B0, 0, 0); PG8_LDB(B1, 0, 1); PG8_SCHED; PG8_LDA(At, 0, 0); PG8_STAGE(PG8_SA(1, 1), a1 + hstepA, voffA);
;             PG8_WAIT_V(8); PG8_WAIT_L(0); PG8_BAR; PG8_MMA(0, 0, At, B0); PG8_MMA(0, 1, At, B1); PG8_BAR; PG8_SCHED;
;             PG8_LDA(At, 0, 1); PG8_STAGE(PG8_SB(0, 0), b2, voffB); PG8_STAGE(PG8_SB(0, 1), b2 + hstepB, voffB); PG8_STAGE(PG8_SA(0, 0), a2, voffA);
;             PG8_WAIT_V(8); PG8_WAIT_L(0); PG8_BAR; PG8_MMA(1, 0, At, B0); PG8_MMA(1, 1, At, B1); PG8_BAR; PG8_SCHED;
.LBB0_347:
	ds_read_b128 v[158:161], v195
	ds_read_b128 v[162:165], v195 offset:1024
	ds_read_b128 v[166:169], v195 offset:2048
	ds_read_b128 v[198:201], v195 offset:3072
	ds_read_b128 v[202:205], v196
	ds_read_b128 v[206:209], v196 offset:1024
	ds_read_b128 v[210:213], v196 offset:2048
	ds_read_b128 v[214:217], v196 offset:3072
	s_add_u32 s59, s16, 0x1fc000
	s_addc_u32 s60, s17, 0
	s_cmp_eq_u32 s58, 28
	s_cselect_b32 s94, s6, s59
	s_cselect_b32 s95, s7, s60
	s_cselect_b32 s92, s14, s55
	s_cselect_b32 s93, s15, s57
	s_add_u32 s82, s94, 0x200000
	s_addc_u32 s83, s95, 0
	s_add_i32 m0, s20, 0xc000
	ds_read_b128 v[218:221], v193
	ds_read_b128 v[222:225], v193 offset:1024
	ds_read_b128 v[226:229], v193 offset:2048
	ds_read_b128 v[230:233], v193 offset:3072
	ds_read_b128 v[234:237], v193 offset:4096
	ds_read_b128 v[238:241], v193 offset:5120
	ds_read_b128 v[242:245], v193 offset:6144
	ds_read_b128 v[246:249], v193 offset:7168
	global_load_lds_dwordx4 v150, s[16:17]
	s_add_i32 m0, s20, 0xe000
	s_nop 0
	global_load_lds_dwordx4 v152, s[16:17]
	s_waitcnt vmcnt(8)
	s_waitcnt lgkmcnt(0)
	s_barrier
	s_waitcnt lgkmcnt(0)
	v_mfma_f32_16x16x32_bf16 v[124:127], v[158:161], v[218:221], v[124:127]
	v_mfma_f32_16x16x32_bf16 v[124:127], v[162:165], v[222:225], v[124:127]
	v_mfma_f32_16x16x32_bf16 v[120:123], v[166:169], v[218:221], v[120:123]
	v_mfma_f32_16x16x32_bf16 v[120:123], v[198:201], v[222:225], v[120:123]
	v_mfma_f32_16x16x32_bf16 v[116:119], v[202:205], v[218:221], v[116:119]
	v_mfma_f32_16x16x32_bf16 v[116:119], v[206:209], v[222:225], v[116:119]
	v_mfma_f32_16x16x32_bf16 v[112:115], v[210:213], v[218:221], v[112:115]
	v_mfma_f32_16x16x32_bf16 v[112:115], v[214:217], v[222:225], v[112:115]
	v_mfma_f32_16x16x32_bf16 v[108:111], v[158:161], v[226:229], v[108:111]
	v_mfma_f32_16x16x32_bf16 v[108:111], v[162:165], v[230:233], v[108:111]
	v_mfma_f32_16x16x32_bf16 v[104:107], v[166:169], v[226:229], v[104:107]
	v_mfma_f32_16x16x32_bf16 v[104:107], v[198:201], v[230:233], v[104:107]
	v_mfma_f32_16x16x32_bf16 v[100:103], v[202:205], v[226:229], v[100:103]
	v_mfma_f32_16x16x32_bf16 v[100:103], v[206:209], v[230:233], v[100:103]
	v_mfma_f32_16x16x32_bf16 v[96:99], v[210:213], v[226:229], v[96:99]
	v_mfma_f32_16x16x32_bf16 v[96:99], v[214:217], v[230:233], v[96:99]
	v_mfma_f32_16x16x32_bf16 v[92:95], v[158:161], v[234:237], v[92:95]
	v_mfma_f32_16x16x32_bf16 v[92:95], v[162:165], v[238:241], v[92:95]
	v_mfma_f32_16x16x32_bf16 v[88:91], v[166:169], v[234:237], v[88:91]
	v_mfma_f32_16x16x32_bf16 v[88:91], v[198:201], v[238:241], v[88:91]
	v_mfma_f32_16x16x32_bf16 v[84:87], v[202:205], v[234:237], v[84:87]
	v_mfma_f32_16x16x32_bf16 v[84:87], v[206:209], v[238:241], v[84:87]
	v_mfma_f32_16x16x32_bf16 v[80:83], v[210:213], v[234:237], v[80:83]
	v_mfma_f32_16x16x32_bf16 v[80:83], v[214:217], v[238:241], v[80:83]
	v_mfma_f32_16x16x32_bf16 v[76:79], v[158:161], v[242:245], v[76:79]
	v_mfma_f32_16x16x32_bf16 v[76:79], v[162:165], v[246:249], v[76:79]
	v_mfma_f32_16x16x32_bf16 v[72:75], v[166:169], v[242:245], v[72:75]
	v_mfma_f32_16x16x32_bf16 v[72:75], v[198:201], v[246:249], v[72:75]
	v_mfma_f32_16x16x32_bf16 v[68:71], v[202:205], v[242:245], v[68:71]
	v_mfma_f32_16x16x32_bf16 v[68:71], v[206:209], v[246:249], v[68:71]
	v_mfma_f32_16x16x32_bf16 v[64:67], v[210:213], v[242:245], v[64:67]
	v_mfma_f32_16x16x32_bf16 v[64:67], v[214:217], v[246:249], v[64:67]
	s_barrier
	s_add_i32 s59, s42, s19
	s_mov_b32 m0, s59
	ds_read_b128 v[218:221], v193 offset:16384
	ds_read_b128 v[222:225], v193 offset:17408
	ds_read_b128 v[226:229], v193 offset:18432
	ds_read_b128 v[230:233], v193 offset:19456
	ds_read_b128 v[234:237], v193 offset:20480
	ds_read_b128 v[238:241], v193 offset:21504
	ds_read_b128 v[242:245], v193 offset:22528
	ds_read_b128 v[246:249], v193 offset:23552
	global_load_lds_dwordx4 v130, s[92:93]
	s_add_i32 m0, s59, 0x2000
	s_add_u32 s60, s92, 0x4000
	s_addc_u32 s61, s93, 0
	s_add_i32 s59, s43, s19
	global_load_lds_dwordx4 v134, s[92:93]
	s_mov_b32 m0, s59
	s_nop 0
	global_load_lds_dwordx4 v130, s[60:61]
	s_add_i32 m0, s59, 0x2000
	s_nop 0
	global_load_lds_dwordx4 v134, s[60:61]
	s_mov_b32 m0, s20
	s_nop 0
	global_load_lds_dwordx4 v128, s[94:95]
	s_mov_b32 m0, s21
	s_nop 0
	global_load_lds_dwordx4 v132, s[94:95]
	s_waitcnt vmcnt(8)
	s_waitcnt lgkmcnt(0)
	s_barrier
	s_waitcnt lgkmcnt(0)
	v_mfma_f32_16x16x32_bf16 v[60:63], v[158:161], v[218:221], v[60:63]
	v_mfma_f32_16x16x32_bf16 v[60:63], v[162:165], v[222:225], v[60:63]
	v_mfma_f32_16x16x32_bf16 v[56:59], v[166:169], v[218:221], v[56:59]
	v_mfma_f32_16x16x32_bf16 v[56:59], v[198:201], v[222:225], v[56:59]
	v_mfma_f32_16x16x32_bf16 v[52:55], v[202:205], v[218:221], v[52:55]
	v_mfma_f32_16x16x32_bf16 v[52:55], v[206:209], v[222:225], v[52:55]
	v_mfma_f32_16x16x32_bf16 v[48:51], v[210:213], v[218:221], v[48:51]
	v_mfma_f32_16x16x32_bf16 v[48:51], v[214:217], v[222:225], v[48:51]
	v_mfma_f32_16x16x32_bf16 v[44:47], v[158:161], v[226:229], v[44:47]
	v_mfma_f32_16x16x32_bf16 v[44:47], v[162:165], v[230:233], v[44:47]
	v_mfma_f32_16x16x32_bf16 v[40:43], v[166:169], v[226:229], v[40:43]
	v_mfma_f32_16x16x32_bf16 v[40:43], v[198:201], v[230:233], v[40:43]
	v_mfma_f32_16x16x32_bf16 v[36:39], v[202:205], v[226:229], v[36:39]
	v_mfma_f32_16x16x32_bf16 v[36:39], v[206:209], v[230:233], v[36:39]
	v_mfma_f32_16x16x32_bf16 v[32:35], v[210:213], v[226:229], v[32:35]
	v_mfma_f32_16x16x32_bf16 v[32:35], v[214:217], v[230:233], v[32:35]
	v_mfma_f32_16x16x32_bf16 v[28:31], v[158:161], v[234:237], v[28:31]
	v_mfma_f32_16x16x32_bf16 v[28:31], v[162:165], v[238:241], v[28:31]
	v_mfma_f32_16x16x32_bf16 v[24:27], v[166:169], v[234:237], v[24:27]
	v_mfma_f32_16x16x32_bf16 v[24:27], v[198:201], v[238:241], v[24:27]
	v_mfma_f32_16x16x32_bf16 v[20:23], v[202:205], v[234:237], v[20:23]
	v_mfma_f32_16x16x32_bf16 v[20:23], v[206:209], v[238:241], v[20:23]
	v_mfma_f32_16x16x32_bf16 v[16:19], v[210:213], v[234:237], v[16:19]
	v_mfma_f32_16x16x32_bf16 v[16:19], v[214:217], v[238:241], v[16:19]
	v_mfma_f32_16x16x32_bf16 v[12:15], v[158:161], v[242:245], v[12:15]
	v_mfma_f32_16x16x32_bf16 v[12:15], v[162:165], v[246:249], v[12:15]
	v_mfma_f32_16x16x32_bf16 v[8:11], v[166:169], v[242:245], v[8:11]
	v_mfma_f32_16x16x32_bf16 v[8:11], v[198:201], v[246:249], v[8:11]
	v_mfma_f32_16x16x32_bf16 v[4:7], v[202:205], v[242:245], v[4:7]
	v_mfma_f32_16x16x32_bf16 v[4:7], v[206:209], v[246:249], v[4:7]
	v_mfma_f32_16x16x32_bf16 v[0:3], v[210:213], v[242:245], v[0:3]
	v_mfma_f32_16x16x32_bf16 v[0:3], v[214:217], v[246:249], v[0:3]
	s_barrier
; #define PG8_STAGE(bufoff, gbase, voff) do { _Pragma("unroll") for (int _i = 0; _i < 2; ++_i) \
;         __builtin_amdgcn_global_load_lds((const unsigned*)((const char*)(gbase) + (voff)[_i]), (LAS unsigned*)(lds + (bufoff) + ldsw + _i * 8192), 16, 0, 0); } while (0)
; #define PG8_LDA(dst, b, h) do { _Pragma("unroll") for (int m = 0; m < 4; ++m) _Pragma("unroll") for (int k = 0; k < 2; ++k) dst[m][k] = *(const LAS bf16x8*)(lds + PG8_SA(b, h) + aoff + m * 2048 + k * 1024); } while (0)
; #define PG8_LDB(dst, b, h) do { _Pragma("unroll") for (int n = 0; n < 2; ++n) _Pragma("unroll") for (int k = 0; k < 2; ++k) dst[n][k] = *(const LAS bf16x8*)(lds + PG8_SB(b, h) + boff + n * 2048 + k * 1024); } while (0)
; #define PG8_MMA(ai, bj, At, Bt) do { __builtin_amdgcn_s_setprio(1); _Pragma("unroll") for (int m = 0; m < 4; ++m) _Pragma("unroll") for (int n = 0; n < 2; ++n) _Pragma("unroll") for (int k = 0; k < 2; ++k) \
;         acc[ai][bj][m][n] = __builtin_amdgcn_mfma_f32_16x16x32_bf16(Bt[n][k], At[m][k], acc[ai][bj][m][n], 0, 0, 0); __builtin_amdgcn_s_setprio(0); } while (0)
; #define PG8_WAIT_V(n) asm volatile("s_waitcnt vmcnt(" #n ")" ::: "memory")
; #define PG8_WAIT_L(n) asm volatile("s_waitcnt lgkmcnt(" #n ")" ::: "memory")
; #define PG8_BAR __builtin_amdgcn_s_barrier()
; #define PG8_SCHED __builtin_amdgcn_sched_barrier(0)
; template <bool ALIGN_EPI, class Epi, class Sched>
; __device__ __forceinline__ void gemm_phase(LAS unsigned char* lds, const int lda, const int ldb, const int K, const Sched& S, const Epi& E, const size_t kstepA = (size_t)(BK * 2), const size_t kstepB = (size_t)(BK * 2)) {
;     ...
;             PG8_LDB(B0, 1, 0); PG8_LDB(B1, 1, 1); PG8_SCHED; PG8_LDA(At, 1, 0); PG8_STAGE(PG8_SA(0, 1), a2 + hstepA, voffA);
;             PG8_WAIT_V(8); PG8_WAIT_L(0); PG8_BAR; PG8_MMA(0, 0, At, B0); PG8_MMA(0, 1, At, B1); PG8_BAR; PG8_SCHED;
;             PG8_LDA(At, 1, 1); PG8_STAGE(PG8_SB(1, 0), b3, voffB); PG8_STAGE(PG8_SB(1, 1), b3 + hstepB, voffB); PG8_STAGE(PG8_SA(1, 0), a3, voffA);
;             PG8_WAIT_V(8); PG8_WAIT_L(0); PG8_BAR; PG8_MMA(1, 0, At, B0); PG8_MMA(1, 1, At, B1); PG8_BAR; PG8_SCHED;
;         }
;         if constexpr (ALIGN_EPI) { if (wr == 0) PG8_BAR; }
	s_add_i32 s59, 0, 0x18000
	v_add_u32_e32 v136, s59, v141
	s_add_i32 s64, 0, 0x1c000
	ds_read_b128 v[158:161], v136
	ds_read_b128 v[162:165], v136 offset:1024
	ds_read_b128 v[166:169], v136 offset:2048
	ds_read_b128 v[198:201], v136 offset:3072
	v_add_u32_e32 v136, s64, v141
	ds_read_b128 v[202:205], v136
	ds_read_b128 v[206:209], v136 offset:1024
	ds_read_b128 v[210:213], v136 offset:2048
	ds_read_b128 v[214:217], v136 offset:3072
	s_add_u32 s60, s94, 0x4000
	s_addc_u32 s61, s95, 0
	s_mov_b32 m0, s22
	ds_read_b128 v[218:221], v193 offset:32768
	ds_read_b128 v[222:225], v193 offset:33792
	ds_read_b128 v[226:229], v193 offset:34816
	ds_read_b128 v[230:233], v193 offset:35840
	ds_read_b128 v[234:237], v193 offset:36864
	ds_read_b128 v[238:241], v193 offset:37888
	ds_read_b128 v[242:245], v193 offset:38912
	ds_read_b128 v[246:249], v193 offset:39936
	global_load_lds_dwordx4 v128, s[60:61]
	s_mov_b32 m0, s23
	s_nop 0
	global_load_lds_dwordx4 v132, s[60:61]
	s_waitcnt vmcnt(8)
	s_waitcnt lgkmcnt(0)
	s_barrier
	s_waitcnt lgkmcnt(0)
	v_mfma_f32_16x16x32_bf16 v[124:127], v[158:161], v[218:221], v[124:127]
	v_mfma_f32_16x16x32_bf16 v[124:127], v[162:165], v[222:225], v[124:127]
	v_mfma_f32_16x16x32_bf16 v[120:123], v[166:169], v[218:221], v[120:123]
	v_mfma_f32_16x16x32_bf16 v[120:123], v[198:201], v[222:225], v[120:123]
	v_mfma_f32_16x16x32_bf16 v[116:119], v[202:205], v[218:221], v[116:119]
	v_mfma_f32_16x16x32_bf16 v[116:119], v[206:209], v[222:225], v[116:119]
	v_mfma_f32_16x16x32_bf16 v[112:115], v[210:213], v[218:221], v[112:115]
	v_mfma_f32_16x16x32_bf16 v[112:115], v[214:217], v[222:225], v[112:115]
	v_mfma_f32_16x16x32_bf16 v[108:111], v[158:161], v[226:229], v[108:111]
	v_mfma_f32_16x16x32_bf16 v[108:111], v[162:165], v[230:233], v[108:111]
	v_mfma_f32_16x16x32_bf16 v[104:107], v[166:169], v[226:229], v[104:107]
	v_mfma_f32_16x16x32_bf16 v[104:107], v[198:201], v[230:233], v[104:107]
	v_mfma_f32_16x16x32_bf16 v[100:103], v[202:205], v[226:229], v[100:103]
	v_mfma_f32_16x16x32_bf16 v[100:103], v[206:209], v[230:233], v[100:103]
	v_mfma_f32_16x16x32_bf16 v[96:99], v[210:213], v[226:229], v[96:99]
	v_mfma_f32_16x16x32_bf16 v[96:99], v[214:217], v[230:233], v[96:99]
	v_mfma_f32_16x16x32_bf16 v[92:95], v[158:161], v[234:237], v[92:95]
	v_mfma_f32_16x16x32_bf16 v[92:95], v[162:165], v[238:241], v[92:95]
	v_mfma_f32_16x16x32_bf16 v[88:91], v[166:169], v[234:237], v[88:91]
	v_mfma_f32_16x16x32_bf16 v[88:91], v[198:201], v[238:241], v[88:91]
	v_mfma_f32_16x16x32_bf16 v[84:87], v[202:205], v[234:237], v[84:87]
	v_mfma_f32_16x16x32_bf16 v[84:87], v[206:209], v[238:241], v[84:87]
	v_mfma_f32_16x16x32_bf16 v[80:83], v[210:213], v[234:237], v[80:83]
	v_mfma_f32_16x16x32_bf16 v[80:83], v[214:217], v[238:241], v[80:83]
	v_mfma_f32_16x16x32_bf16 v[76:79], v[158:161], v[242:245], v[76:79]
	v_mfma_f32_16x16x32_bf16 v[76:79], v[162:165], v[246:249], v[76:79]
	v_mfma_f32_16x16x32_bf16 v[72:75], v[166:169], v[242:245], v[72:75]
	v_mfma_f32_16x16x32_bf16 v[72:75], v[198:201], v[246:249], v[72:75]
	v_mfma_f32_16x16x32_bf16 v[68:71], v[202:205], v[242:245], v[68:71]
	v_mfma_f32_16x16x32_bf16 v[68:71], v[206:209], v[246:249], v[68:71]
	v_mfma_f32_16x16x32_bf16 v[64:67], v[210:213], v[242:245], v[64:67]
	v_mfma_f32_16x16x32_bf16 v[64:67], v[214:217], v[246:249], v[64:67]
	s_barrier
	s_add_u32 s60, s92, 0x80000
	s_addc_u32 s61, s93, 0
	s_add_i32 s59, s59, s19
	s_mov_b32 m0, s59
	ds_read_b128 v[218:221], v193 offset:49152
	ds_read_b128 v[222:225], v193 offset:50176
	ds_read_b128 v[226:229], v193 offset:51200
	ds_read_b128 v[230:233], v193 offset:52224
	ds_read_b128 v[234:237], v193 offset:53248
	ds_read_b128 v[238:241], v193 offset:54272
	ds_read_b128 v[242:245], v193 offset:55296
	ds_read_b128 v[246:249], v193 offset:56320
	global_load_lds_dwordx4 v130, s[60:61]
	s_add_i32 m0, s59, 0x2000
	s_nop 0
	global_load_lds_dwordx4 v134, s[60:61]
	s_add_u32 s60, s92, 0x84000
	s_addc_u32 s61, s93, 0
	s_add_i32 s59, s64, s19
	s_mov_b32 m0, s59
	s_nop 0
	global_load_lds_dwordx4 v130, s[60:61]
	s_add_i32 m0, s59, 0x2000
	s_nop 0
	global_load_lds_dwordx4 v134, s[60:61]
	s_mov_b32 m0, s30
	s_nop 0
	global_load_lds_dwordx4 v128, s[82:83]
	s_mov_b32 m0, s31
	s_nop 0
	global_load_lds_dwordx4 v132, s[82:83]
	s_waitcnt vmcnt(8)
	s_waitcnt lgkmcnt(0)
	s_barrier
	s_waitcnt lgkmcnt(0)
	v_mfma_f32_16x16x32_bf16 v[60:63], v[158:161], v[218:221], v[60:63]
	v_mfma_f32_16x16x32_bf16 v[60:63], v[162:165], v[222:225], v[60:63]
	v_mfma_f32_16x16x32_bf16 v[56:59], v[166:169], v[218:221], v[56:59]
	v_mfma_f32_16x16x32_bf16 v[56:59], v[198:201], v[222:225], v[56:59]
	v_mfma_f32_16x16x32_bf16 v[52:55], v[202:205], v[218:221], v[52:55]
	v_mfma_f32_16x16x32_bf16 v[52:55], v[206:209], v[222:225], v[52:55]
	v_mfma_f32_16x16x32_bf16 v[48:51], v[210:213], v[218:221], v[48:51]
	v_mfma_f32_16x16x32_bf16 v[48:51], v[214:217], v[222:225], v[48:51]
	v_mfma_f32_16x16x32_bf16 v[44:47], v[158:161], v[226:229], v[44:47]
	v_mfma_f32_16x16x32_bf16 v[44:47], v[162:165], v[230:233], v[44:47]
	v_mfma_f32_16x16x32_bf16 v[40:43], v[166:169], v[226:229], v[40:43]
	v_mfma_f32_16x16x32_bf16 v[40:43], v[198:201], v[230:233], v[40:43]
	v_mfma_f32_16x16x32_bf16 v[36:39], v[202:205], v[226:229], v[36:39]
	v_mfma_f32_16x16x32_bf16 v[36:39], v[206:209], v[230:233], v[36:39]
	v_mfma_f32_16x16x32_bf16 v[32:35], v[210:213], v[226:229], v[32:35]
	v_mfma_f32_16x16x32_bf16 v[32:35], v[214:217], v[230:233], v[32:35]
	v_mfma_f32_16x16x32_bf16 v[28:31], v[158:161], v[234:237], v[28:31]
	v_mfma_f32_16x16x32_bf16 v[28:31], v[162:165], v[238:241], v[28:31]
	v_mfma_f32_16x16x32_bf16 v[24:27], v[166:169], v[234:237], v[24:27]
	v_mfma_f32_16x16x32_bf16 v[24:27], v[198:201], v[238:241], v[24:27]
	v_mfma_f32_16x16x32_bf16 v[20:23], v[202:205], v[234:237], v[20:23]
	v_mfma_f32_16x16x32_bf16 v[20:23], v[206:209], v[238:241], v[20:23]
	v_mfma_f32_16x16x32_bf16 v[16:19], v[210:213], v[234:237], v[16:19]
	v_mfma_f32_16x16x32_bf16 v[16:19], v[214:217], v[238:241], v[16:19]
	v_mfma_f32_16x16x32_bf16 v[12:15], v[158:161], v[242:245], v[12:15]
	v_mfma_f32_16x16x32_bf16 v[12:15], v[162:165], v[246:249], v[12:15]
	v_mfma_f32_16x16x32_bf16 v[8:11], v[166:169], v[242:245], v[8:11]
	v_mfma_f32_16x16x32_bf16 v[8:11], v[198:201], v[246:249], v[8:11]
	v_mfma_f32_16x16x32_bf16 v[4:7], v[202:205], v[242:245], v[4:7]
	v_mfma_f32_16x16x32_bf16 v[4:7], v[206:209], v[246:249], v[4:7]
	v_mfma_f32_16x16x32_bf16 v[0:3], v[210:213], v[242:245], v[0:3]
	v_mfma_f32_16x16x32_bf16 v[0:3], v[214:217], v[246:249], v[0:3]
	s_barrier
	s_add_i32 s58, s58, 2
	s_add_u32 s55, s55, 0x100000
	s_addc_u32 s57, s57, 0
	s_add_u32 s16, s16, 0x400000
	s_addc_u32 s17, s17, 0
	s_cmp_gt_u32 s58, 29
	s_cbranch_scc0 .LBB0_347
	s_and_b64 vcc, exec, s[68:69]
	s_cbranch_vccz .LBB0_350
	s_barrier

; #define PG8_STAGE(bufoff, gbase, voff) do { _Pragma("unroll") for (int _i = 0; _i < 2; ++_i) \
;         __builtin_amdgcn_global_load_lds((const unsigned*)((const char*)(gbase) + (voff)[_i]), (LAS unsigned*)(lds + (bufoff) + ldsw + _i * 8192), 16, 0, 0); } while (0)
; #define PG8_LDA(dst, b, h) do { _Pragma("unroll") for (int m = 0; m < 4; ++m) _Pragma("unroll") for (int k = 0; k < 2; ++k) dst[m][k] = *(const LAS bf16x8*)(lds + PG8_SA(b, h) + aoff + m * 2048 + k * 1024); } while (0)
; #define PG8_LDB(dst, b, h) do { _Pragma("unroll") for (int n = 0; n < 2; ++n) _Pragma("unroll") for (int k = 0; k < 2; ++k) dst[n][k] = *(const LAS bf16x8*)(lds + PG8_SB(b, h) + boff + n * 2048 + k * 1024); } while (0)
; #define PG8_MMA(ai, bj, At, Bt) do { __builtin_amdgcn_s_setprio(1); _Pragma("unroll") for (int m = 0; m < 4; ++m) _Pragma("unroll") for (int n = 0; n < 2; ++n) _Pragma("unroll") for (int k = 0; k < 2; ++k) \
;         acc[ai][bj][m][n] = __builtin_amdgcn_mfma_f32_16x16x32_bf16(Bt[n][k], At[m][k], acc[ai][bj][m][n], 0, 0, 0); __builtin_amdgcn_s_setprio(0); } while (0)
; #define PG8_WAIT_V(n) asm volatile("s_waitcnt vmcnt(" #n ")" ::: "memory")
; #define PG8_WAIT_L(n) asm volatile("s_waitcnt lgkmcnt(" #n ")" ::: "memory")
; template <bool ALIGN_EPI, class Epi, class Sched>
; __device__ __forceinline__ void gemm_phase(LAS unsigned char* lds, const int lda, const int ldb, const int K, const Sched& S, const Epi& E, const size_t kstepA = (size_t)(BK * 2), const size_t kstepB = (size_t)(BK * 2)) {
;     ...
;         for (int t = 0; t < nt; t += 2) {
;             const bool last = (t == nt - 2);
;             const char* a1 = cA + (size_t)(t + 1) * kstepA;
;             const char* a2 = last ? nA : cA + (size_t)(t + 2) * kstepA; const char* b2 = last ? nB : cB + (size_t)(t + 2) * kstep;
;             const char* a3 = a2 + kstepA; const char* b3 = b2 + kstep;
;             PG8_LDB(B0, 0, 0); PG8_LDB(B1, 0, 1); PG8_SCHED; PG8_LDA(At, 0, 0); PG8_STAGE(PG8_SA(1, 1), a1 + hstepA, voffA);
;             PG8_WAIT_V(8); PG8_WAIT_L(0); PG8_BAR; PG8_MMA(0, 0, At, B0); PG8_MMA(0, 1, At, B1); PG8_BAR; PG8_SCHED;
;             PG8_LDA(At, 0, 1); PG8_STAGE(PG8_SB(0, 0), b2, voffB); PG8_STAGE(PG8_SB(0, 1), b2 + hstepB, voffB); PG8_STAGE(PG8_SA(0, 0), a2, voffA);
;             PG8_WAIT_V(8); PG8_WAIT_L(0); PG8_BAR; PG8_MMA(1, 0, At, B0); PG8_MMA(1, 1, At, B1); PG8_BAR; PG8_SCHED;
.LBB0_726:
	ds_read_b128 v[88:91], v219
	ds_read_b128 v[92:95], v219 offset:1024
	ds_read_b128 v[112:115], v219 offset:2048
	ds_read_b128 v[116:119], v219 offset:3072
	ds_read_b128 v[144:147], v220
	ds_read_b128 v[148:151], v220 offset:1024
	ds_read_b128 v[152:155], v220 offset:2048
	ds_read_b128 v[156:159], v220 offset:3072
	s_add_u32 s14, s12, 0x1fc000
	s_addc_u32 s15, s13, 0
	s_cmp_eq_u32 s67, 28
	s_cselect_b32 s20, s0, s14
	s_cselect_b32 s21, s1, s15
	s_cselect_b32 s16, s6, s22
	s_cselect_b32 s17, s7, s23
	s_add_u32 s14, s20, 0x200000
	s_addc_u32 s15, s21, 0
	s_add_i32 m0, s19, 0xc000
	ds_read_b128 v[160:163], v221
	ds_read_b128 v[164:167], v221 offset:1024
	ds_read_b128 v[188:191], v221 offset:2048
	ds_read_b128 v[192:195], v221 offset:3072
	ds_read_b128 v[196:199], v221 offset:4096
	ds_read_b128 v[200:203], v221 offset:5120
	ds_read_b128 v[204:207], v221 offset:6144
	ds_read_b128 v[208:211], v221 offset:7168
	global_load_lds_dwordx4 v178, s[12:13]
	s_add_i32 m0, s19, 0xe000
	s_nop 0
	global_load_lds_dwordx4 v180, s[12:13]
	s_waitcnt vmcnt(8)
	s_waitcnt lgkmcnt(0)
	s_barrier
	s_waitcnt lgkmcnt(0)
	v_mfma_f32_16x16x32_bf16 v[140:143], v[88:91], v[160:163], v[140:143]
	v_mfma_f32_16x16x32_bf16 v[140:143], v[92:95], v[164:167], v[140:143]
	v_mfma_f32_16x16x32_bf16 v[136:139], v[112:115], v[160:163], v[136:139]
	v_mfma_f32_16x16x32_bf16 v[136:139], v[116:119], v[164:167], v[136:139]
	v_mfma_f32_16x16x32_bf16 v[132:135], v[144:147], v[160:163], v[132:135]
	v_mfma_f32_16x16x32_bf16 v[132:135], v[148:151], v[164:167], v[132:135]
	v_mfma_f32_16x16x32_bf16 v[128:131], v[152:155], v[160:163], v[128:131]
	v_mfma_f32_16x16x32_bf16 v[128:131], v[156:159], v[164:167], v[128:131]
	v_mfma_f32_16x16x32_bf16 v[124:127], v[88:91], v[188:191], v[124:127]
	v_mfma_f32_16x16x32_bf16 v[124:127], v[92:95], v[192:195], v[124:127]
	v_mfma_f32_16x16x32_bf16 v[120:123], v[112:115], v[188:191], v[120:123]
	v_mfma_f32_16x16x32_bf16 v[120:123], v[116:119], v[192:195], v[120:123]
	v_mfma_f32_16x16x32_bf16 v[108:111], v[144:147], v[188:191], v[108:111]
	v_mfma_f32_16x16x32_bf16 v[108:111], v[148:151], v[192:195], v[108:111]
	v_mfma_f32_16x16x32_bf16 v[104:107], v[152:155], v[188:191], v[104:107]
	v_mfma_f32_16x16x32_bf16 v[104:107], v[156:159], v[192:195], v[104:107]
	v_mfma_f32_16x16x32_bf16 v[100:103], v[88:91], v[196:199], v[100:103]
	v_mfma_f32_16x16x32_bf16 v[100:103], v[92:95], v[200:203], v[100:103]
	v_mfma_f32_16x16x32_bf16 v[96:99], v[112:115], v[196:199], v[96:99]
	v_mfma_f32_16x16x32_bf16 v[96:99], v[116:119], v[200:203], v[96:99]
	v_mfma_f32_16x16x32_bf16 v[84:87], v[144:147], v[196:199], v[84:87]
	v_mfma_f32_16x16x32_bf16 v[84:87], v[148:151], v[200:203], v[84:87]
	v_mfma_f32_16x16x32_bf16 v[80:83], v[152:155], v[196:199], v[80:83]
	v_mfma_f32_16x16x32_bf16 v[80:83], v[156:159], v[200:203], v[80:83]
	v_mfma_f32_16x16x32_bf16 v[76:79], v[88:91], v[204:207], v[76:79]
	v_mfma_f32_16x16x32_bf16 v[76:79], v[92:95], v[208:211], v[76:79]
	v_mfma_f32_16x16x32_bf16 v[72:75], v[112:115], v[204:207], v[72:75]
	v_mfma_f32_16x16x32_bf16 v[72:75], v[116:119], v[208:211], v[72:75]
	v_mfma_f32_16x16x32_bf16 v[68:71], v[144:147], v[204:207], v[68:71]
	v_mfma_f32_16x16x32_bf16 v[68:71], v[148:151], v[208:211], v[68:71]
	v_mfma_f32_16x16x32_bf16 v[64:67], v[152:155], v[204:207], v[64:67]
	v_mfma_f32_16x16x32_bf16 v[64:67], v[156:159], v[208:211], v[64:67]
	s_barrier
	s_add_i32 s69, s65, s18
	s_mov_b32 m0, s69
	ds_read_b128 v[160:163], v221 offset:16384
	ds_read_b128 v[164:167], v221 offset:17408
	ds_read_b128 v[188:191], v221 offset:18432
	ds_read_b128 v[192:195], v221 offset:19456
	ds_read_b128 v[196:199], v221 offset:20480
	ds_read_b128 v[200:203], v221 offset:21504
	ds_read_b128 v[204:207], v221 offset:22528
	ds_read_b128 v[208:211], v221 offset:23552
	global_load_lds_dwordx4 v170, s[16:17]
	s_add_i32 m0, s69, 0x2000
	s_add_u32 s78, s16, 0x4000
	s_addc_u32 s79, s17, 0
	s_add_i32 s69, s74, s18
	global_load_lds_dwordx4 v174, s[16:17]
	s_mov_b32 m0, s69
	s_nop 0
	global_load_lds_dwordx4 v170, s[78:79]
	s_add_i32 m0, s69, 0x2000
	s_nop 0
	global_load_lds_dwordx4 v174, s[78:79]
	s_mov_b32 m0, s19
	s_nop 0
	global_load_lds_dwordx4 v168, s[20:21]
	s_mov_b32 m0, s30
	s_nop 0
	global_load_lds_dwordx4 v172, s[20:21]
	s_waitcnt vmcnt(8)
	s_waitcnt lgkmcnt(0)
	s_barrier
	s_waitcnt lgkmcnt(0)
	v_mfma_f32_16x16x32_bf16 v[60:63], v[88:91], v[160:163], v[60:63]
	v_mfma_f32_16x16x32_bf16 v[60:63], v[92:95], v[164:167], v[60:63]
	v_mfma_f32_16x16x32_bf16 v[56:59], v[112:115], v[160:163], v[56:59]
	v_mfma_f32_16x16x32_bf16 v[56:59], v[116:119], v[164:167], v[56:59]
	v_mfma_f32_16x16x32_bf16 v[52:55], v[144:147], v[160:163], v[52:55]
	v_mfma_f32_16x16x32_bf16 v[52:55], v[148:151], v[164:167], v[52:55]
	v_mfma_f32_16x16x32_bf16 v[48:51], v[152:155], v[160:163], v[48:51]
	v_mfma_f32_16x16x32_bf16 v[48:51], v[156:159], v[164:167], v[48:51]
	v_mfma_f32_16x16x32_bf16 v[44:47], v[88:91], v[188:191], v[44:47]
	v_mfma_f32_16x16x32_bf16 v[44:47], v[92:95], v[192:195], v[44:47]
	v_mfma_f32_16x16x32_bf16 v[40:43], v[112:115], v[188:191], v[40:43]
	v_mfma_f32_16x16x32_bf16 v[40:43], v[116:119], v[192:195], v[40:43]
	v_mfma_f32_16x16x32_bf16 v[36:39], v[144:147], v[188:191], v[36:39]
	v_mfma_f32_16x16x32_bf16 v[36:39], v[148:151], v[192:195], v[36:39]
	v_mfma_f32_16x16x32_bf16 v[32:35], v[152:155], v[188:191], v[32:35]
	v_mfma_f32_16x16x32_bf16 v[32:35], v[156:159], v[192:195], v[32:35]
	v_mfma_f32_16x16x32_bf16 v[28:31], v[88:91], v[196:199], v[28:31]
	v_mfma_f32_16x16x32_bf16 v[28:31], v[92:95], v[200:203], v[28:31]
	v_mfma_f32_16x16x32_bf16 v[24:27], v[112:115], v[196:199], v[24:27]
	v_mfma_f32_16x16x32_bf16 v[24:27], v[116:119], v[200:203], v[24:27]
	v_mfma_f32_16x16x32_bf16 v[20:23], v[144:147], v[196:199], v[20:23]
	v_mfma_f32_16x16x32_bf16 v[20:23], v[148:151], v[200:203], v[20:23]
	v_mfma_f32_16x16x32_bf16 v[16:19], v[152:155], v[196:199], v[16:19]
	v_mfma_f32_16x16x32_bf16 v[16:19], v[156:159], v[200:203], v[16:19]
	v_mfma_f32_16x16x32_bf16 v[12:15], v[88:91], v[204:207], v[12:15]
	v_mfma_f32_16x16x32_bf16 v[12:15], v[92:95], v[208:211], v[12:15]
	v_mfma_f32_16x16x32_bf16 v[8:11], v[112:115], v[204:207], v[8:11]
	v_mfma_f32_16x16x32_bf16 v[8:11], v[116:119], v[208:211], v[8:11]
	v_mfma_f32_16x16x32_bf16 v[4:7], v[144:147], v[204:207], v[4:7]
	v_mfma_f32_16x16x32_bf16 v[4:7], v[148:151], v[208:211], v[4:7]
	v_mfma_f32_16x16x32_bf16 v[0:3], v[152:155], v[204:207], v[0:3]
	v_mfma_f32_16x16x32_bf16 v[0:3], v[156:159], v[208:211], v[0:3]
	s_barrier
; #define PG8_STAGE(bufoff, gbase, voff) do { _Pragma("unroll") for (int _i = 0; _i < 2; ++_i) \
;         __builtin_amdgcn_global_load_lds((const unsigned*)((const char*)(gbase) + (voff)[_i]), (LAS unsigned*)(lds + (bufoff) + ldsw + _i * 8192), 16, 0, 0); } while (0)
; #define PG8_LDA(dst, b, h) do { _Pragma("unroll") for (int m = 0; m < 4; ++m) _Pragma("unroll") for (int k = 0; k < 2; ++k) dst[m][k] = *(const LAS bf16x8*)(lds + PG8_SA(b, h) + aoff + m * 2048 + k * 1024); } while (0)
; #define PG8_LDB(dst, b, h) do { _Pragma("unroll") for (int n = 0; n < 2; ++n) _Pragma("unroll") for (int k = 0; k < 2; ++k) dst[n][k] = *(const LAS bf16x8*)(lds + PG8_SB(b, h) + boff + n * 2048 + k * 1024); } while (0)
; #define PG8_MMA(ai, bj, At, Bt) do { __builtin_amdgcn_s_setprio(1); _Pragma("unroll") for (int m = 0; m < 4; ++m) _Pragma("unroll") for (int n = 0; n < 2; ++n) _Pragma("unroll") for (int k = 0; k < 2; ++k) \
;         acc[ai][bj][m][n] = __builtin_amdgcn_mfma_f32_16x16x32_bf16(Bt[n][k], At[m][k], acc[ai][bj][m][n], 0, 0, 0); __builtin_amdgcn_s_setprio(0); } while (0)
; #define PG8_WAIT_V(n) asm volatile("s_waitcnt vmcnt(" #n ")" ::: "memory")
; #define PG8_WAIT_L(n) asm volatile("s_waitcnt lgkmcnt(" #n ")" ::: "memory")
; #define PG8_BAR __builtin_amdgcn_s_barrier()
; #define PG8_SCHED __builtin_amdgcn_sched_barrier(0)
; template <bool ALIGN_EPI, class Epi, class Sched>
; __device__ __forceinline__ void gemm_phase(LAS unsigned char* lds, const int lda, const int ldb, const int K, const Sched& S, const Epi& E, const size_t kstepA = (size_t)(BK * 2), const size_t kstepB = (size_t)(BK * 2)) {
;     ...
;             PG8_LDB(B0, 1, 0); PG8_LDB(B1, 1, 1); PG8_SCHED; PG8_LDA(At, 1, 0); PG8_STAGE(PG8_SA(0, 1), a2 + hstepA, voffA);
;             PG8_WAIT_V(8); PG8_WAIT_L(0); PG8_BAR; PG8_MMA(0, 0, At, B0); PG8_MMA(0, 1, At, B1); PG8_BAR; PG8_SCHED;
;             PG8_LDA(At, 1, 1); PG8_STAGE(PG8_SB(1, 0), b3, voffB); PG8_STAGE(PG8_SB(1, 1), b3 + hstepB, voffB); PG8_STAGE(PG8_SA(1, 0), a3, voffA);
;             PG8_WAIT_V(8); PG8_WAIT_L(0); PG8_BAR; PG8_MMA(1, 0, At, B0); PG8_MMA(1, 1, At, B1); PG8_BAR; PG8_SCHED;
;         }
;         if constexpr (ALIGN_EPI) { if (wr == 0) PG8_BAR; }
	s_add_i32 s69, 0, 0x18000
	s_add_i32 s77, 0, 0x1c000
	v_add_u32_e32 v116, s69, v218
	v_add_u32_e32 v156, s77, v218
	ds_read_b128 v[88:91], v116
	ds_read_b128 v[92:95], v116 offset:1024
	ds_read_b128 v[112:115], v116 offset:2048
	ds_read_b128 v[116:119], v116 offset:3072
	ds_read_b128 v[144:147], v156
	ds_read_b128 v[148:151], v156 offset:1024
	ds_read_b128 v[152:155], v156 offset:2048
	ds_read_b128 v[156:159], v156 offset:3072
	s_add_u32 s20, s20, 0x4000
	s_addc_u32 s21, s21, 0
	s_mov_b32 m0, s33
	ds_read_b128 v[160:163], v221 offset:32768
	ds_read_b128 v[164:167], v221 offset:33792
	ds_read_b128 v[188:191], v221 offset:34816
	ds_read_b128 v[192:195], v221 offset:35840
	ds_read_b128 v[196:199], v221 offset:36864
	ds_read_b128 v[200:203], v221 offset:37888
	ds_read_b128 v[204:207], v221 offset:38912
	ds_read_b128 v[208:211], v221 offset:39936
	global_load_lds_dwordx4 v168, s[20:21]
	s_mov_b32 m0, s42
	s_nop 0
	global_load_lds_dwordx4 v172, s[20:21]
	s_waitcnt vmcnt(8)
	s_waitcnt lgkmcnt(0)
	s_barrier
	s_waitcnt lgkmcnt(0)
	v_mfma_f32_16x16x32_bf16 v[140:143], v[88:91], v[160:163], v[140:143]
	v_mfma_f32_16x16x32_bf16 v[140:143], v[92:95], v[164:167], v[140:143]
	v_mfma_f32_16x16x32_bf16 v[136:139], v[112:115], v[160:163], v[136:139]
	v_mfma_f32_16x16x32_bf16 v[136:139], v[116:119], v[164:167], v[136:139]
	v_mfma_f32_16x16x32_bf16 v[132:135], v[144:147], v[160:163], v[132:135]
	v_mfma_f32_16x16x32_bf16 v[132:135], v[148:151], v[164:167], v[132:135]
	v_mfma_f32_16x16x32_bf16 v[128:131], v[152:155], v[160:163], v[128:131]
	v_mfma_f32_16x16x32_bf16 v[128:131], v[156:159], v[164:167], v[128:131]
	v_mfma_f32_16x16x32_bf16 v[124:127], v[88:91], v[188:191], v[124:127]
	v_mfma_f32_16x16x32_bf16 v[124:127], v[92:95], v[192:195], v[124:127]
	v_mfma_f32_16x16x32_bf16 v[120:123], v[112:115], v[188:191], v[120:123]
	v_mfma_f32_16x16x32_bf16 v[120:123], v[116:119], v[192:195], v[120:123]
	v_mfma_f32_16x16x32_bf16 v[108:111], v[144:147], v[188:191], v[108:111]
	v_mfma_f32_16x16x32_bf16 v[108:111], v[148:151], v[192:195], v[108:111]
	v_mfma_f32_16x16x32_bf16 v[104:107], v[152:155], v[188:191], v[104:107]
	v_mfma_f32_16x16x32_bf16 v[104:107], v[156:159], v[192:195], v[104:107]
	v_mfma_f32_16x16x32_bf16 v[100:103], v[88:91], v[196:199], v[100:103]
	v_mfma_f32_16x16x32_bf16 v[100:103], v[92:95], v[200:203], v[100:103]
	v_mfma_f32_16x16x32_bf16 v[96:99], v[112:115], v[196:199], v[96:99]
	v_mfma_f32_16x16x32_bf16 v[96:99], v[116:119], v[200:203], v[96:99]
	v_mfma_f32_16x16x32_bf16 v[84:87], v[144:147], v[196:199], v[84:87]
	v_mfma_f32_16x16x32_bf16 v[84:87], v[148:151], v[200:203], v[84:87]
	v_mfma_f32_16x16x32_bf16 v[80:83], v[152:155], v[196:199], v[80:83]
	v_mfma_f32_16x16x32_bf16 v[80:83], v[156:159], v[200:203], v[80:83]
	v_mfma_f32_16x16x32_bf16 v[76:79], v[88:91], v[204:207], v[76:79]
	v_mfma_f32_16x16x32_bf16 v[76:79], v[92:95], v[208:211], v[76:79]
	v_mfma_f32_16x16x32_bf16 v[72:75], v[112:115], v[204:207], v[72:75]
	v_mfma_f32_16x16x32_bf16 v[72:75], v[116:119], v[208:211], v[72:75]
	v_mfma_f32_16x16x32_bf16 v[68:71], v[144:147], v[204:207], v[68:71]
	v_mfma_f32_16x16x32_bf16 v[68:71], v[148:151], v[208:211], v[68:71]
	v_mfma_f32_16x16x32_bf16 v[64:67], v[152:155], v[204:207], v[64:67]
	v_mfma_f32_16x16x32_bf16 v[64:67], v[156:159], v[208:211], v[64:67]
	s_barrier
	s_add_u32 s20, s16, 0x40000
	s_addc_u32 s21, s17, 0
	s_add_i32 s69, s69, s18
	s_mov_b32 m0, s69
	ds_read_b128 v[160:163], v221 offset:49152
	ds_read_b128 v[164:167], v221 offset:50176
	ds_read_b128 v[188:191], v221 offset:51200
	ds_read_b128 v[192:195], v221 offset:52224
	ds_read_b128 v[196:199], v221 offset:53248
	ds_read_b128 v[200:203], v221 offset:54272
	ds_read_b128 v[204:207], v221 offset:55296
	ds_read_b128 v[208:211], v221 offset:56320
	global_load_lds_dwordx4 v170, s[20:21]
	s_add_i32 m0, s69, 0x2000
	s_add_u32 s16, s16, 0x44000
	global_load_lds_dwordx4 v174, s[20:21]
	s_addc_u32 s17, s17, 0
	s_add_i32 s20, s77, s18
	s_mov_b32 m0, s20
	s_nop 0
	global_load_lds_dwordx4 v170, s[16:17]
	s_add_i32 m0, s20, 0x2000
	s_nop 0
	global_load_lds_dwordx4 v174, s[16:17]
	s_mov_b32 m0, s51
	s_nop 0
	global_load_lds_dwordx4 v168, s[14:15]
	s_mov_b32 m0, s64
	s_nop 0
	global_load_lds_dwordx4 v172, s[14:15]
	s_waitcnt vmcnt(8)
	s_waitcnt lgkmcnt(0)
	s_barrier
	s_waitcnt lgkmcnt(0)
	v_mfma_f32_16x16x32_bf16 v[60:63], v[88:91], v[160:163], v[60:63]
	v_mfma_f32_16x16x32_bf16 v[60:63], v[92:95], v[164:167], v[60:63]
	v_mfma_f32_16x16x32_bf16 v[56:59], v[112:115], v[160:163], v[56:59]
	v_mfma_f32_16x16x32_bf16 v[56:59], v[116:119], v[164:167], v[56:59]
	v_mfma_f32_16x16x32_bf16 v[52:55], v[144:147], v[160:163], v[52:55]
	v_mfma_f32_16x16x32_bf16 v[52:55], v[148:151], v[164:167], v[52:55]
	v_mfma_f32_16x16x32_bf16 v[48:51], v[152:155], v[160:163], v[48:51]
	v_mfma_f32_16x16x32_bf16 v[48:51], v[156:159], v[164:167], v[48:51]
	v_mfma_f32_16x16x32_bf16 v[44:47], v[88:91], v[188:191], v[44:47]
	v_mfma_f32_16x16x32_bf16 v[44:47], v[92:95], v[192:195], v[44:47]
	v_mfma_f32_16x16x32_bf16 v[40:43], v[112:115], v[188:191], v[40:43]
	v_mfma_f32_16x16x32_bf16 v[40:43], v[116:119], v[192:195], v[40:43]
	v_mfma_f32_16x16x32_bf16 v[36:39], v[144:147], v[188:191], v[36:39]
	v_mfma_f32_16x16x32_bf16 v[36:39], v[148:151], v[192:195], v[36:39]
	v_mfma_f32_16x16x32_bf16 v[32:35], v[152:155], v[188:191], v[32:35]
	v_mfma_f32_16x16x32_bf16 v[32:35], v[156:159], v[192:195], v[32:35]
	v_mfma_f32_16x16x32_bf16 v[28:31], v[88:91], v[196:199], v[28:31]
	v_mfma_f32_16x16x32_bf16 v[28:31], v[92:95], v[200:203], v[28:31]
	v_mfma_f32_16x16x32_bf16 v[24:27], v[112:115], v[196:199], v[24:27]
	v_mfma_f32_16x16x32_bf16 v[24:27], v[116:119], v[200:203], v[24:27]
	v_mfma_f32_16x16x32_bf16 v[20:23], v[144:147], v[196:199], v[20:23]
	v_mfma_f32_16x16x32_bf16 v[20:23], v[148:151], v[200:203], v[20:23]
	v_mfma_f32_16x16x32_bf16 v[16:19], v[152:155], v[196:199], v[16:19]
	v_mfma_f32_16x16x32_bf16 v[16:19], v[156:159], v[200:203], v[16:19]
	v_mfma_f32_16x16x32_bf16 v[12:15], v[88:91], v[204:207], v[12:15]
	v_mfma_f32_16x16x32_bf16 v[12:15], v[92:95], v[208:211], v[12:15]
	v_mfma_f32_16x16x32_bf16 v[8:11], v[112:115], v[204:207], v[8:11]
	v_mfma_f32_16x16x32_bf16 v[8:11], v[116:119], v[208:211], v[8:11]
	v_mfma_f32_16x16x32_bf16 v[4:7], v[144:147], v[204:207], v[4:7]
	v_mfma_f32_16x16x32_bf16 v[4:7], v[148:151], v[208:211], v[4:7]
	v_mfma_f32_16x16x32_bf16 v[0:3], v[152:155], v[204:207], v[0:3]
	v_mfma_f32_16x16x32_bf16 v[0:3], v[156:159], v[208:211], v[0:3]
	s_barrier
	s_add_i32 s67, s67, 2
	s_add_u32 s22, s22, 0x80000
	s_addc_u32 s23, s23, 0
	s_add_u32 s12, s12, 0x400000
	s_addc_u32 s13, s13, 0
	s_cmp_gt_u32 s67, 29
	s_cbranch_scc0 .LBB0_726
	s_and_b64 vcc, exec, s[56:57]
	s_cbranch_vccz .LBB0_729
	s_barrier

; #define PG8_STAGE(bufoff, gbase, voff) do { _Pragma("unroll") for (int _i = 0; _i < 2; ++_i) \
;         __builtin_amdgcn_global_load_lds((const unsigned*)((const char*)(gbase) + (voff)[_i]), (LAS unsigned*)(lds + (bufoff) + ldsw + _i * 8192), 16, 0, 0); } while (0)
; #define PG8_LDA(dst, b, h) do { _Pragma("unroll") for (int m = 0; m < 4; ++m) _Pragma("unroll") for (int k = 0; k < 2; ++k) dst[m][k] = *(const LAS bf16x8*)(lds + PG8_SA(b, h) + aoff + m * 2048 + k * 1024); } while (0)
; #define PG8_LDB(dst, b, h) do { _Pragma("unroll") for (int n = 0; n < 2; ++n) _Pragma("unroll") for (int k = 0; k < 2; ++k) dst[n][k] = *(const LAS bf16x8*)(lds + PG8_SB(b, h) + boff + n * 2048 + k * 1024); } while (0)
; #define PG8_MMA(ai, bj, At, Bt) do { __builtin_amdgcn_s_setprio(1); _Pragma("unroll") for (int m = 0; m < 4; ++m) _Pragma("unroll") for (int n = 0; n < 2; ++n) _Pragma("unroll") for (int k = 0; k < 2; ++k) \
;         acc[ai][bj][m][n] = __builtin_amdgcn_mfma_f32_16x16x32_bf16(Bt[n][k], At[m][k], acc[ai][bj][m][n], 0, 0, 0); __builtin_amdgcn_s_setprio(0); } while (0)
; #define PG8_WAIT_V(n) asm volatile("s_waitcnt vmcnt(" #n ")" ::: "memory")
; #define PG8_WAIT_L(n) asm volatile("s_waitcnt lgkmcnt(" #n ")" ::: "memory")
; template <bool ALIGN_EPI, class Epi, class Sched>
; __device__ __forceinline__ void gemm_phase(LAS unsigned char* lds, const int lda, const int ldb, const int K, const Sched& S, const Epi& E, const size_t kstepA = (size_t)(BK * 2), const size_t kstepB = (size_t)(BK * 2)) {
;     ...
;         for (int t = 0; t < nt; t += 2) {
;             const bool last = (t == nt - 2);
;             const char* a1 = cA + (size_t)(t + 1) * kstepA;
;             const char* a2 = last ? nA : cA + (size_t)(t + 2) * kstepA; const char* b2 = last ? nB : cB + (size_t)(t + 2) * kstep;
;             const char* a3 = a2 + kstepA; const char* b3 = b2 + kstep;
;             PG8_LDB(B0, 0, 0); PG8_LDB(B1, 0, 1); PG8_SCHED; PG8_LDA(At, 0, 0); PG8_STAGE(PG8_SA(1, 1), a1 + hstepA, voffA);
;             PG8_WAIT_V(8); PG8_WAIT_L(0); PG8_BAR; PG8_MMA(0, 0, At, B0); PG8_MMA(0, 1, At, B1); PG8_BAR; PG8_SCHED;
;             PG8_LDA(At, 0, 1); PG8_STAGE(PG8_SB(0, 0), b2, voffB); PG8_STAGE(PG8_SB(0, 1), b2 + hstepB, voffB); PG8_STAGE(PG8_SA(0, 0), a2, voffA);
;             PG8_WAIT_V(8); PG8_WAIT_L(0); PG8_BAR; PG8_MMA(1, 0, At, B0); PG8_MMA(1, 1, At, B1); PG8_BAR; PG8_SCHED;
.LBB0_952:
	ds_read_b128 v[88:91], v219
	ds_read_b128 v[92:95], v219 offset:1024
	ds_read_b128 v[112:115], v219 offset:2048
	ds_read_b128 v[116:119], v219 offset:3072
	ds_read_b128 v[144:147], v220
	ds_read_b128 v[148:151], v220 offset:1024
	ds_read_b128 v[152:155], v220 offset:2048
	ds_read_b128 v[156:159], v220 offset:3072
	s_add_u32 s14, s12, 0x1fc000
	s_addc_u32 s15, s13, 0
	s_cmp_eq_u32 s61, 12
	s_cselect_b32 s20, s0, s14
	s_cselect_b32 s21, s1, s15
	s_cselect_b32 s16, s6, s22
	s_cselect_b32 s17, s7, s23
	s_add_u32 s14, s20, 0x200000
	s_addc_u32 s15, s21, 0
	s_add_i32 m0, s19, 0xc000
	ds_read_b128 v[160:163], v221
	ds_read_b128 v[164:167], v221 offset:1024
	ds_read_b128 v[188:191], v221 offset:2048
	ds_read_b128 v[192:195], v221 offset:3072
	ds_read_b128 v[196:199], v221 offset:4096
	ds_read_b128 v[200:203], v221 offset:5120
	ds_read_b128 v[204:207], v221 offset:6144
	ds_read_b128 v[208:211], v221 offset:7168
	global_load_lds_dwordx4 v178, s[12:13]
	s_add_i32 m0, s19, 0xe000
	s_nop 0
	global_load_lds_dwordx4 v180, s[12:13]
	s_waitcnt vmcnt(8)
	s_waitcnt lgkmcnt(0)
	s_barrier
	s_waitcnt lgkmcnt(0)
	v_mfma_f32_16x16x32_bf16 v[140:143], v[88:91], v[160:163], v[140:143]
	v_mfma_f32_16x16x32_bf16 v[140:143], v[92:95], v[164:167], v[140:143]
	v_mfma_f32_16x16x32_bf16 v[136:139], v[112:115], v[160:163], v[136:139]
	v_mfma_f32_16x16x32_bf16 v[136:139], v[116:119], v[164:167], v[136:139]
	v_mfma_f32_16x16x32_bf16 v[132:135], v[144:147], v[160:163], v[132:135]
	v_mfma_f32_16x16x32_bf16 v[132:135], v[148:151], v[164:167], v[132:135]
	v_mfma_f32_16x16x32_bf16 v[128:131], v[152:155], v[160:163], v[128:131]
	v_mfma_f32_16x16x32_bf16 v[128:131], v[156:159], v[164:167], v[128:131]
	v_mfma_f32_16x16x32_bf16 v[124:127], v[88:91], v[188:191], v[124:127]
	v_mfma_f32_16x16x32_bf16 v[124:127], v[92:95], v[192:195], v[124:127]
	v_mfma_f32_16x16x32_bf16 v[120:123], v[112:115], v[188:191], v[120:123]
	v_mfma_f32_16x16x32_bf16 v[120:123], v[116:119], v[192:195], v[120:123]
	v_mfma_f32_16x16x32_bf16 v[108:111], v[144:147], v[188:191], v[108:111]
	v_mfma_f32_16x16x32_bf16 v[108:111], v[148:151], v[192:195], v[108:111]
	v_mfma_f32_16x16x32_bf16 v[104:107], v[152:155], v[188:191], v[104:107]
	v_mfma_f32_16x16x32_bf16 v[104:107], v[156:159], v[192:195], v[104:107]
	v_mfma_f32_16x16x32_bf16 v[100:103], v[88:91], v[196:199], v[100:103]
	v_mfma_f32_16x16x32_bf16 v[100:103], v[92:95], v[200:203], v[100:103]
	v_mfma_f32_16x16x32_bf16 v[96:99], v[112:115], v[196:199], v[96:99]
	v_mfma_f32_16x16x32_bf16 v[96:99], v[116:119], v[200:203], v[96:99]
	v_mfma_f32_16x16x32_bf16 v[84:87], v[144:147], v[196:199], v[84:87]
	v_mfma_f32_16x16x32_bf16 v[84:87], v[148:151], v[200:203], v[84:87]
	v_mfma_f32_16x16x32_bf16 v[80:83], v[152:155], v[196:199], v[80:83]
	v_mfma_f32_16x16x32_bf16 v[80:83], v[156:159], v[200:203], v[80:83]
	v_mfma_f32_16x16x32_bf16 v[76:79], v[88:91], v[204:207], v[76:79]
	v_mfma_f32_16x16x32_bf16 v[76:79], v[92:95], v[208:211], v[76:79]
	v_mfma_f32_16x16x32_bf16 v[72:75], v[112:115], v[204:207], v[72:75]
	v_mfma_f32_16x16x32_bf16 v[72:75], v[116:119], v[208:211], v[72:75]
	v_mfma_f32_16x16x32_bf16 v[68:71], v[144:147], v[204:207], v[68:71]
	v_mfma_f32_16x16x32_bf16 v[68:71], v[148:151], v[208:211], v[68:71]
	v_mfma_f32_16x16x32_bf16 v[64:67], v[152:155], v[204:207], v[64:67]
	v_mfma_f32_16x16x32_bf16 v[64:67], v[156:159], v[208:211], v[64:67]
	s_barrier
	s_add_i32 s63, s71, s18
	s_mov_b32 m0, s63
	ds_read_b128 v[160:163], v221 offset:16384
	ds_read_b128 v[164:167], v221 offset:17408
	ds_read_b128 v[188:191], v221 offset:18432
	ds_read_b128 v[192:195], v221 offset:19456
	ds_read_b128 v[196:199], v221 offset:20480
	ds_read_b128 v[200:203], v221 offset:21504
	ds_read_b128 v[204:207], v221 offset:22528
	ds_read_b128 v[208:211], v221 offset:23552
	global_load_lds_dwordx4 v170, s[16:17]
	s_add_i32 m0, s63, 0x2000
	s_add_u32 s76, s16, 0x4000
	s_addc_u32 s77, s17, 0
	s_add_i32 s63, s72, s18
	global_load_lds_dwordx4 v174, s[16:17]
	s_mov_b32 m0, s63
	s_nop 0
	global_load_lds_dwordx4 v170, s[76:77]
	s_add_i32 m0, s63, 0x2000
	s_nop 0
	global_load_lds_dwordx4 v174, s[76:77]
	s_mov_b32 m0, s19
	s_nop 0
	global_load_lds_dwordx4 v168, s[20:21]
	s_mov_b32 m0, s33
	s_nop 0
	global_load_lds_dwordx4 v172, s[20:21]
	s_waitcnt vmcnt(8)
	s_waitcnt lgkmcnt(0)
	s_barrier
	s_waitcnt lgkmcnt(0)
	v_mfma_f32_16x16x32_bf16 v[60:63], v[88:91], v[160:163], v[60:63]
	v_mfma_f32_16x16x32_bf16 v[60:63], v[92:95], v[164:167], v[60:63]
	v_mfma_f32_16x16x32_bf16 v[56:59], v[112:115], v[160:163], v[56:59]
	v_mfma_f32_16x16x32_bf16 v[56:59], v[116:119], v[164:167], v[56:59]
	v_mfma_f32_16x16x32_bf16 v[52:55], v[144:147], v[160:163], v[52:55]
	v_mfma_f32_16x16x32_bf16 v[52:55], v[148:151], v[164:167], v[52:55]
	v_mfma_f32_16x16x32_bf16 v[48:51], v[152:155], v[160:163], v[48:51]
	v_mfma_f32_16x16x32_bf16 v[48:51], v[156:159], v[164:167], v[48:51]
	v_mfma_f32_16x16x32_bf16 v[44:47], v[88:91], v[188:191], v[44:47]
	v_mfma_f32_16x16x32_bf16 v[44:47], v[92:95], v[192:195], v[44:47]
	v_mfma_f32_16x16x32_bf16 v[40:43], v[112:115], v[188:191], v[40:43]
	v_mfma_f32_16x16x32_bf16 v[40:43], v[116:119], v[192:195], v[40:43]
	v_mfma_f32_16x16x32_bf16 v[36:39], v[144:147], v[188:191], v[36:39]
	v_mfma_f32_16x16x32_bf16 v[36:39], v[148:151], v[192:195], v[36:39]
	v_mfma_f32_16x16x32_bf16 v[32:35], v[152:155], v[188:191], v[32:35]
	v_mfma_f32_16x16x32_bf16 v[32:35], v[156:159], v[192:195], v[32:35]
	v_mfma_f32_16x16x32_bf16 v[28:31], v[88:91], v[196:199], v[28:31]
	v_mfma_f32_16x16x32_bf16 v[28:31], v[92:95], v[200:203], v[28:31]
	v_mfma_f32_16x16x32_bf16 v[24:27], v[112:115], v[196:199], v[24:27]
	v_mfma_f32_16x16x32_bf16 v[24:27], v[116:119], v[200:203], v[24:27]
	v_mfma_f32_16x16x32_bf16 v[20:23], v[144:147], v[196:199], v[20:23]
	v_mfma_f32_16x16x32_bf16 v[20:23], v[148:151], v[200:203], v[20:23]
	v_mfma_f32_16x16x32_bf16 v[16:19], v[152:155], v[196:199], v[16:19]
	v_mfma_f32_16x16x32_bf16 v[16:19], v[156:159], v[200:203], v[16:19]
	v_mfma_f32_16x16x32_bf16 v[12:15], v[88:91], v[204:207], v[12:15]
	v_mfma_f32_16x16x32_bf16 v[12:15], v[92:95], v[208:211], v[12:15]
	v_mfma_f32_16x16x32_bf16 v[8:11], v[112:115], v[204:207], v[8:11]
	v_mfma_f32_16x16x32_bf16 v[8:11], v[116:119], v[208:211], v[8:11]
	v_mfma_f32_16x16x32_bf16 v[4:7], v[144:147], v[204:207], v[4:7]
	v_mfma_f32_16x16x32_bf16 v[4:7], v[148:151], v[208:211], v[4:7]
	v_mfma_f32_16x16x32_bf16 v[0:3], v[152:155], v[204:207], v[0:3]
	v_mfma_f32_16x16x32_bf16 v[0:3], v[156:159], v[208:211], v[0:3]
	s_barrier
; #define PG8_STAGE(bufoff, gbase, voff) do { _Pragma("unroll") for (int _i = 0; _i < 2; ++_i) \
;         __builtin_amdgcn_global_load_lds((const unsigned*)((const char*)(gbase) + (voff)[_i]), (LAS unsigned*)(lds + (bufoff) + ldsw + _i * 8192), 16, 0, 0); } while (0)
; #define PG8_LDA(dst, b, h) do { _Pragma("unroll") for (int m = 0; m < 4; ++m) _Pragma("unroll") for (int k = 0; k < 2; ++k) dst[m][k] = *(const LAS bf16x8*)(lds + PG8_SA(b, h) + aoff + m * 2048 + k * 1024); } while (0)
; #define PG8_LDB(dst, b, h) do { _Pragma("unroll") for (int n = 0; n < 2; ++n) _Pragma("unroll") for (int k = 0; k < 2; ++k) dst[n][k] = *(const LAS bf16x8*)(lds + PG8_SB(b, h) + boff + n * 2048 + k * 1024); } while (0)
; #define PG8_MMA(ai, bj, At, Bt) do { __builtin_amdgcn_s_setprio(1); _Pragma("unroll") for (int m = 0; m < 4; ++m) _Pragma("unroll") for (int n = 0; n < 2; ++n) _Pragma("unroll") for (int k = 0; k < 2; ++k) \
;         acc[ai][bj][m][n] = __builtin_amdgcn_mfma_f32_16x16x32_bf16(Bt[n][k], At[m][k], acc[ai][bj][m][n], 0, 0, 0); __builtin_amdgcn_s_setprio(0); } while (0)
; #define PG8_WAIT_V(n) asm volatile("s_waitcnt vmcnt(" #n ")" ::: "memory")
; #define PG8_WAIT_L(n) asm volatile("s_waitcnt lgkmcnt(" #n ")" ::: "memory")
; #define PG8_BAR __builtin_amdgcn_s_barrier()
; #define PG8_SCHED __builtin_amdgcn_sched_barrier(0)
; template <bool ALIGN_EPI, class Epi, class Sched>
; __device__ __forceinline__ void gemm_phase(LAS unsigned char* lds, const int lda, const int ldb, const int K, const Sched& S, const Epi& E, const size_t kstepA = (size_t)(BK * 2), const size_t kstepB = (size_t)(BK * 2)) {
;     ...
;             PG8_LDB(B0, 1, 0); PG8_LDB(B1, 1, 1); PG8_SCHED; PG8_LDA(At, 1, 0); PG8_STAGE(PG8_SA(0, 1), a2 + hstepA, voffA);
;             PG8_WAIT_V(8); PG8_WAIT_L(0); PG8_BAR; PG8_MMA(0, 0, At, B0); PG8_MMA(0, 1, At, B1); PG8_BAR; PG8_SCHED;
;             PG8_LDA(At, 1, 1); PG8_STAGE(PG8_SB(1, 0), b3, voffB); PG8_STAGE(PG8_SB(1, 1), b3 + hstepB, voffB); PG8_STAGE(PG8_SA(1, 0), a3, voffA);
;             PG8_WAIT_V(8); PG8_WAIT_L(0); PG8_BAR; PG8_MMA(1, 0, At, B0); PG8_MMA(1, 1, At, B1); PG8_BAR; PG8_SCHED;
;         }
;         if constexpr (ALIGN_EPI) { if (wr == 0) PG8_BAR; }
	s_add_i32 s63, 0, 0x18000
	s_add_i32 s75, 0, 0x1c000
	v_add_u32_e32 v116, s63, v218
	v_add_u32_e32 v156, s75, v218
	ds_read_b128 v[88:91], v116
	ds_read_b128 v[92:95], v116 offset:1024
	ds_read_b128 v[112:115], v116 offset:2048
	ds_read_b128 v[116:119], v116 offset:3072
	ds_read_b128 v[144:147], v156
	ds_read_b128 v[148:151], v156 offset:1024
	ds_read_b128 v[152:155], v156 offset:2048
	ds_read_b128 v[156:159], v156 offset:3072
	s_add_u32 s20, s20, 0x4000
	s_addc_u32 s21, s21, 0
	s_mov_b32 m0, s42
	ds_read_b128 v[160:163], v221 offset:32768
	ds_read_b128 v[164:167], v221 offset:33792
	ds_read_b128 v[188:191], v221 offset:34816
	ds_read_b128 v[192:195], v221 offset:35840
	ds_read_b128 v[196:199], v221 offset:36864
	ds_read_b128 v[200:203], v221 offset:37888
	ds_read_b128 v[204:207], v221 offset:38912
	ds_read_b128 v[208:211], v221 offset:39936
	global_load_lds_dwordx4 v168, s[20:21]
	s_mov_b32 m0, s43
	s_nop 0
	global_load_lds_dwordx4 v172, s[20:21]
	s_waitcnt vmcnt(8)
	s_waitcnt lgkmcnt(0)
	s_barrier
	s_waitcnt lgkmcnt(0)
	v_mfma_f32_16x16x32_bf16 v[140:143], v[88:91], v[160:163], v[140:143]
	v_mfma_f32_16x16x32_bf16 v[140:143], v[92:95], v[164:167], v[140:143]
	v_mfma_f32_16x16x32_bf16 v[136:139], v[112:115], v[160:163], v[136:139]
	v_mfma_f32_16x16x32_bf16 v[136:139], v[116:119], v[164:167], v[136:139]
	v_mfma_f32_16x16x32_bf16 v[132:135], v[144:147], v[160:163], v[132:135]
	v_mfma_f32_16x16x32_bf16 v[132:135], v[148:151], v[164:167], v[132:135]
	v_mfma_f32_16x16x32_bf16 v[128:131], v[152:155], v[160:163], v[128:131]
	v_mfma_f32_16x16x32_bf16 v[128:131], v[156:159], v[164:167], v[128:131]
	v_mfma_f32_16x16x32_bf16 v[124:127], v[88:91], v[188:191], v[124:127]
	v_mfma_f32_16x16x32_bf16 v[124:127], v[92:95], v[192:195], v[124:127]
	v_mfma_f32_16x16x32_bf16 v[120:123], v[112:115], v[188:191], v[120:123]
	v_mfma_f32_16x16x32_bf16 v[120:123], v[116:119], v[192:195], v[120:123]
	v_mfma_f32_16x16x32_bf16 v[108:111], v[144:147], v[188:191], v[108:111]
	v_mfma_f32_16x16x32_bf16 v[108:111], v[148:151], v[192:195], v[108:111]
	v_mfma_f32_16x16x32_bf16 v[104:107], v[152:155], v[188:191], v[104:107]
	v_mfma_f32_16x16x32_bf16 v[104:107], v[156:159], v[192:195], v[104:107]
	v_mfma_f32_16x16x32_bf16 v[100:103], v[88:91], v[196:199], v[100:103]
	v_mfma_f32_16x16x32_bf16 v[100:103], v[92:95], v[200:203], v[100:103]
	v_mfma_f32_16x16x32_bf16 v[96:99], v[112:115], v[196:199], v[96:99]
	v_mfma_f32_16x16x32_bf16 v[96:99], v[116:119], v[200:203], v[96:99]
	v_mfma_f32_16x16x32_bf16 v[84:87], v[144:147], v[196:199], v[84:87]
	v_mfma_f32_16x16x32_bf16 v[84:87], v[148:151], v[200:203], v[84:87]
	v_mfma_f32_16x16x32_bf16 v[80:83], v[152:155], v[196:199], v[80:83]
	v_mfma_f32_16x16x32_bf16 v[80:83], v[156:159], v[200:203], v[80:83]
	v_mfma_f32_16x16x32_bf16 v[76:79], v[88:91], v[204:207], v[76:79]
	v_mfma_f32_16x16x32_bf16 v[76:79], v[92:95], v[208:211], v[76:79]
	v_mfma_f32_16x16x32_bf16 v[72:75], v[112:115], v[204:207], v[72:75]
	v_mfma_f32_16x16x32_bf16 v[72:75], v[116:119], v[208:211], v[72:75]
	v_mfma_f32_16x16x32_bf16 v[68:71], v[144:147], v[204:207], v[68:71]
	v_mfma_f32_16x16x32_bf16 v[68:71], v[148:151], v[208:211], v[68:71]
	v_mfma_f32_16x16x32_bf16 v[64:67], v[152:155], v[204:207], v[64:67]
	v_mfma_f32_16x16x32_bf16 v[64:67], v[156:159], v[208:211], v[64:67]
	s_barrier
	s_add_u32 s20, s16, 0x40000
	s_addc_u32 s21, s17, 0
	s_add_i32 s63, s63, s18
	s_mov_b32 m0, s63
	ds_read_b128 v[160:163], v221 offset:49152
	ds_read_b128 v[164:167], v221 offset:50176
	ds_read_b128 v[188:191], v221 offset:51200
	ds_read_b128 v[192:195], v221 offset:52224
	ds_read_b128 v[196:199], v221 offset:53248
	ds_read_b128 v[200:203], v221 offset:54272
	ds_read_b128 v[204:207], v221 offset:55296
	ds_read_b128 v[208:211], v221 offset:56320
	global_load_lds_dwordx4 v170, s[20:21]
	s_add_i32 m0, s63, 0x2000
	s_add_u32 s16, s16, 0x44000
	global_load_lds_dwordx4 v174, s[20:21]
	s_addc_u32 s17, s17, 0
	s_add_i32 s20, s75, s18
	s_mov_b32 m0, s20
	s_nop 0
	global_load_lds_dwordx4 v170, s[16:17]
	s_add_i32 m0, s20, 0x2000
	s_nop 0
	global_load_lds_dwordx4 v174, s[16:17]
	s_mov_b32 m0, s64
	s_nop 0
	global_load_lds_dwordx4 v168, s[14:15]
	s_mov_b32 m0, s65
	s_nop 0
	global_load_lds_dwordx4 v172, s[14:15]
	s_waitcnt vmcnt(8)
	s_waitcnt lgkmcnt(0)
	s_barrier
	s_waitcnt lgkmcnt(0)
	v_mfma_f32_16x16x32_bf16 v[60:63], v[88:91], v[160:163], v[60:63]
	v_mfma_f32_16x16x32_bf16 v[60:63], v[92:95], v[164:167], v[60:63]
	v_mfma_f32_16x16x32_bf16 v[56:59], v[112:115], v[160:163], v[56:59]
	v_mfma_f32_16x16x32_bf16 v[56:59], v[116:119], v[164:167], v[56:59]
	v_mfma_f32_16x16x32_bf16 v[52:55], v[144:147], v[160:163], v[52:55]
	v_mfma_f32_16x16x32_bf16 v[52:55], v[148:151], v[164:167], v[52:55]
	v_mfma_f32_16x16x32_bf16 v[48:51], v[152:155], v[160:163], v[48:51]
	v_mfma_f32_16x16x32_bf16 v[48:51], v[156:159], v[164:167], v[48:51]
	v_mfma_f32_16x16x32_bf16 v[44:47], v[88:91], v[188:191], v[44:47]
	v_mfma_f32_16x16x32_bf16 v[44:47], v[92:95], v[192:195], v[44:47]
	v_mfma_f32_16x16x32_bf16 v[40:43], v[112:115], v[188:191], v[40:43]
	v_mfma_f32_16x16x32_bf16 v[40:43], v[116:119], v[192:195], v[40:43]
	v_mfma_f32_16x16x32_bf16 v[36:39], v[144:147], v[188:191], v[36:39]
	v_mfma_f32_16x16x32_bf16 v[36:39], v[148:151], v[192:195], v[36:39]
	v_mfma_f32_16x16x32_bf16 v[32:35], v[152:155], v[188:191], v[32:35]
	v_mfma_f32_16x16x32_bf16 v[32:35], v[156:159], v[192:195], v[32:35]
	v_mfma_f32_16x16x32_bf16 v[28:31], v[88:91], v[196:199], v[28:31]
	v_mfma_f32_16x16x32_bf16 v[28:31], v[92:95], v[200:203], v[28:31]
	v_mfma_f32_16x16x32_bf16 v[24:27], v[112:115], v[196:199], v[24:27]
	v_mfma_f32_16x16x32_bf16 v[24:27], v[116:119], v[200:203], v[24:27]
	v_mfma_f32_16x16x32_bf16 v[20:23], v[144:147], v[196:199], v[20:23]
	v_mfma_f32_16x16x32_bf16 v[20:23], v[148:151], v[200:203], v[20:23]
	v_mfma_f32_16x16x32_bf16 v[16:19], v[152:155], v[196:199], v[16:19]
	v_mfma_f32_16x16x32_bf16 v[16:19], v[156:159], v[200:203], v[16:19]
	v_mfma_f32_16x16x32_bf16 v[12:15], v[88:91], v[204:207], v[12:15]
	v_mfma_f32_16x16x32_bf16 v[12:15], v[92:95], v[208:211], v[12:15]
	v_mfma_f32_16x16x32_bf16 v[8:11], v[112:115], v[204:207], v[8:11]
	v_mfma_f32_16x16x32_bf16 v[8:11], v[116:119], v[208:211], v[8:11]
	v_mfma_f32_16x16x32_bf16 v[4:7], v[144:147], v[204:207], v[4:7]
	v_mfma_f32_16x16x32_bf16 v[4:7], v[148:151], v[208:211], v[4:7]
	v_mfma_f32_16x16x32_bf16 v[0:3], v[152:155], v[204:207], v[0:3]
	v_mfma_f32_16x16x32_bf16 v[0:3], v[156:159], v[208:211], v[0:3]
	s_barrier
	s_add_i32 s61, s61, 2
	s_add_u32 s22, s22, 0x80000
	s_addc_u32 s23, s23, 0
	s_add_u32 s12, s12, 0x400000
	s_addc_u32 s13, s13, 0
	s_cmp_gt_u32 s61, 13
	s_cbranch_scc0 .LBB0_952
	s_and_b64 vcc, exec, s[52:53]
	s_cbranch_vccz .LBB0_955
	s_barrier

; #define PG8_STAGE(bufoff, gbase, voff) do { _Pragma("unroll") for (int _i = 0; _i < 2; ++_i) \
;         __builtin_amdgcn_global_load_lds((const unsigned*)((const char*)(gbase) + (voff)[_i]), (LAS unsigned*)(lds + (bufoff) + ldsw + _i * 8192), 16, 0, 0); } while (0)
; #define PG8_LDA(dst, b, h) do { _Pragma("unroll") for (int m = 0; m < 4; ++m) _Pragma("unroll") for (int k = 0; k < 2; ++k) dst[m][k] = *(const LAS bf16x8*)(lds + PG8_SA(b, h) + aoff + m * 2048 + k * 1024); } while (0)
; #define PG8_LDB(dst, b, h) do { _Pragma("unroll") for (int n = 0; n < 2; ++n) _Pragma("unroll") for (int k = 0; k < 2; ++k) dst[n][k] = *(const LAS bf16x8*)(lds + PG8_SB(b, h) + boff + n * 2048 + k * 1024); } while (0)
; #define PG8_MMA(ai, bj, At, Bt) do { __builtin_amdgcn_s_setprio(1); _Pragma("unroll") for (int m = 0; m < 4; ++m) _Pragma("unroll") for (int n = 0; n < 2; ++n) _Pragma("unroll") for (int k = 0; k < 2; ++k) \
;         acc[ai][bj][m][n] = __builtin_amdgcn_mfma_f32_16x16x32_bf16(Bt[n][k], At[m][k], acc[ai][bj][m][n], 0, 0, 0); __builtin_amdgcn_s_setprio(0); } while (0)
; #define PG8_WAIT_V(n) asm volatile("s_waitcnt vmcnt(" #n ")" ::: "memory")
; #define PG8_WAIT_L(n) asm volatile("s_waitcnt lgkmcnt(" #n ")" ::: "memory")
; template <bool ALIGN_EPI, class Epi, class Sched>
; __device__ __forceinline__ void gemm_phase(LAS unsigned char* lds, const int lda, const int ldb, const int K, const Sched& S, const Epi& E, const size_t kstepA = (size_t)(BK * 2), const size_t kstepB = (size_t)(BK * 2)) {
;     ...
;         for (int t = 0; t < nt; t += 2) {
;             const bool last = (t == nt - 2);
;             const char* a1 = cA + (size_t)(t + 1) * kstepA;
;             const char* a2 = last ? nA : cA + (size_t)(t + 2) * kstepA; const char* b2 = last ? nB : cB + (size_t)(t + 2) * kstep;
;             const char* a3 = a2 + kstepA; const char* b3 = b2 + kstep;
;             PG8_LDB(B0, 0, 0); PG8_LDB(B1, 0, 1); PG8_SCHED; PG8_LDA(At, 0, 0); PG8_STAGE(PG8_SA(1, 1), a1 + hstepA, voffA);
;             PG8_WAIT_V(8); PG8_WAIT_L(0); PG8_BAR; PG8_MMA(0, 0, At, B0); PG8_MMA(0, 1, At, B1); PG8_BAR; PG8_SCHED;
;             PG8_LDA(At, 0, 1); PG8_STAGE(PG8_SB(0, 0), b2, voffB); PG8_STAGE(PG8_SB(0, 1), b2 + hstepB, voffB); PG8_STAGE(PG8_SA(0, 0), a2, voffA);
;             PG8_WAIT_V(8); PG8_WAIT_L(0); PG8_BAR; PG8_MMA(1, 0, At, B0); PG8_MMA(1, 1, At, B1); PG8_BAR; PG8_SCHED;
.LBB0_1044:
	ds_read_b128 v[148:151], v168
	ds_read_b128 v[172:175], v168 offset:1024
	ds_read_b128 v[176:179], v168 offset:2048
	ds_read_b128 v[180:183], v168 offset:3072
	ds_read_b128 v[186:189], v169
	ds_read_b128 v[190:193], v169 offset:1024
	ds_read_b128 v[194:197], v169 offset:2048
	ds_read_b128 v[198:201], v169 offset:3072
	s_add_u32 s48, s46, 0x1fc000
	s_addc_u32 s49, s47, 0
	s_cmp_eq_u32 s15, 28
	s_cselect_b32 s54, s22, s48
	s_cselect_b32 s55, s23, s49
	s_cselect_b32 s52, s44, s9
	s_cselect_b32 s53, s45, s13
	s_add_u32 s48, s54, 0x200000
	s_addc_u32 s49, s55, 0
	s_add_i32 m0, s29, 0xc000
	ds_read_b128 v[202:205], v170
	ds_read_b128 v[206:209], v170 offset:1024
	ds_read_b128 v[210:213], v170 offset:2048
	ds_read_b128 v[214:217], v170 offset:3072
	ds_read_b128 v[218:221], v170 offset:4096
	ds_read_b128 v[222:225], v170 offset:5120
	ds_read_b128 v[226:229], v170 offset:6144
	ds_read_b128 v[230:233], v170 offset:7168
	global_load_lds_dwordx4 v140, s[46:47]
	s_add_i32 m0, s29, 0xe000
	s_nop 0
	global_load_lds_dwordx4 v142, s[46:47]
	s_waitcnt vmcnt(8)
	s_waitcnt lgkmcnt(0)
	s_barrier
	s_waitcnt lgkmcnt(0)
	v_mfma_f32_16x16x32_bf16 v[124:127], v[148:151], v[202:205], v[124:127]
	v_mfma_f32_16x16x32_bf16 v[124:127], v[172:175], v[206:209], v[124:127]
	v_mfma_f32_16x16x32_bf16 v[120:123], v[176:179], v[202:205], v[120:123]
	v_mfma_f32_16x16x32_bf16 v[120:123], v[180:183], v[206:209], v[120:123]
	v_mfma_f32_16x16x32_bf16 v[116:119], v[186:189], v[202:205], v[116:119]
	v_mfma_f32_16x16x32_bf16 v[116:119], v[190:193], v[206:209], v[116:119]
	v_mfma_f32_16x16x32_bf16 v[112:115], v[194:197], v[202:205], v[112:115]
	v_mfma_f32_16x16x32_bf16 v[112:115], v[198:201], v[206:209], v[112:115]
	v_mfma_f32_16x16x32_bf16 v[108:111], v[148:151], v[210:213], v[108:111]
	v_mfma_f32_16x16x32_bf16 v[108:111], v[172:175], v[214:217], v[108:111]
	v_mfma_f32_16x16x32_bf16 v[104:107], v[176:179], v[210:213], v[104:107]
	v_mfma_f32_16x16x32_bf16 v[104:107], v[180:183], v[214:217], v[104:107]
	v_mfma_f32_16x16x32_bf16 v[100:103], v[186:189], v[210:213], v[100:103]
	v_mfma_f32_16x16x32_bf16 v[100:103], v[190:193], v[214:217], v[100:103]
	v_mfma_f32_16x16x32_bf16 v[96:99], v[194:197], v[210:213], v[96:99]
	v_mfma_f32_16x16x32_bf16 v[96:99], v[198:201], v[214:217], v[96:99]
	v_mfma_f32_16x16x32_bf16 v[92:95], v[148:151], v[218:221], v[92:95]
	v_mfma_f32_16x16x32_bf16 v[92:95], v[172:175], v[222:225], v[92:95]
	v_mfma_f32_16x16x32_bf16 v[88:91], v[176:179], v[218:221], v[88:91]
	v_mfma_f32_16x16x32_bf16 v[88:91], v[180:183], v[222:225], v[88:91]
	v_mfma_f32_16x16x32_bf16 v[84:87], v[186:189], v[218:221], v[84:87]
	v_mfma_f32_16x16x32_bf16 v[84:87], v[190:193], v[222:225], v[84:87]
	v_mfma_f32_16x16x32_bf16 v[80:83], v[194:197], v[218:221], v[80:83]
	v_mfma_f32_16x16x32_bf16 v[80:83], v[198:201], v[222:225], v[80:83]
	v_mfma_f32_16x16x32_bf16 v[76:79], v[148:151], v[226:229], v[76:79]
	v_mfma_f32_16x16x32_bf16 v[76:79], v[172:175], v[230:233], v[76:79]
	v_mfma_f32_16x16x32_bf16 v[72:75], v[176:179], v[226:229], v[72:75]
	v_mfma_f32_16x16x32_bf16 v[72:75], v[180:183], v[230:233], v[72:75]
	v_mfma_f32_16x16x32_bf16 v[68:71], v[186:189], v[226:229], v[68:71]
	v_mfma_f32_16x16x32_bf16 v[68:71], v[190:193], v[230:233], v[68:71]
	v_mfma_f32_16x16x32_bf16 v[64:67], v[194:197], v[226:229], v[64:67]
	v_mfma_f32_16x16x32_bf16 v[64:67], v[198:201], v[230:233], v[64:67]
	s_barrier
	s_add_i32 s61, s57, s19
	s_mov_b32 m0, s61
	ds_read_b128 v[202:205], v170 offset:16384
	ds_read_b128 v[206:209], v170 offset:17408
	ds_read_b128 v[210:213], v170 offset:18432
	ds_read_b128 v[214:217], v170 offset:19456
	ds_read_b128 v[218:221], v170 offset:20480
	ds_read_b128 v[222:225], v170 offset:21504
	ds_read_b128 v[226:229], v170 offset:22528
	ds_read_b128 v[230:233], v170 offset:23552
	global_load_lds_dwordx4 v130, s[52:53]
	s_add_i32 m0, s61, 0x2000
	s_add_u32 s62, s52, 0x4000
	s_addc_u32 s63, s53, 0
	s_add_i32 s61, s58, s19
	global_load_lds_dwordx4 v134, s[52:53]
	s_mov_b32 m0, s61
	s_nop 0
	global_load_lds_dwordx4 v130, s[62:63]
	s_add_i32 m0, s61, 0x2000
	s_nop 0
	global_load_lds_dwordx4 v134, s[62:63]
	s_mov_b32 m0, s29
	s_nop 0
	global_load_lds_dwordx4 v128, s[54:55]
	s_mov_b32 m0, s30
	s_nop 0
	global_load_lds_dwordx4 v132, s[54:55]
	s_waitcnt vmcnt(8)
	s_waitcnt lgkmcnt(0)
	s_barrier
	s_waitcnt lgkmcnt(0)
	v_mfma_f32_16x16x32_bf16 v[60:63], v[148:151], v[202:205], v[60:63]
	v_mfma_f32_16x16x32_bf16 v[60:63], v[172:175], v[206:209], v[60:63]
	v_mfma_f32_16x16x32_bf16 v[56:59], v[176:179], v[202:205], v[56:59]
	v_mfma_f32_16x16x32_bf16 v[56:59], v[180:183], v[206:209], v[56:59]
	v_mfma_f32_16x16x32_bf16 v[52:55], v[186:189], v[202:205], v[52:55]
	v_mfma_f32_16x16x32_bf16 v[52:55], v[190:193], v[206:209], v[52:55]
	v_mfma_f32_16x16x32_bf16 v[48:51], v[194:197], v[202:205], v[48:51]
	v_mfma_f32_16x16x32_bf16 v[48:51], v[198:201], v[206:209], v[48:51]
	v_mfma_f32_16x16x32_bf16 v[44:47], v[148:151], v[210:213], v[44:47]
	v_mfma_f32_16x16x32_bf16 v[44:47], v[172:175], v[214:217], v[44:47]
	v_mfma_f32_16x16x32_bf16 v[40:43], v[176:179], v[210:213], v[40:43]
	v_mfma_f32_16x16x32_bf16 v[40:43], v[180:183], v[214:217], v[40:43]
	v_mfma_f32_16x16x32_bf16 v[36:39], v[186:189], v[210:213], v[36:39]
	v_mfma_f32_16x16x32_bf16 v[36:39], v[190:193], v[214:217], v[36:39]
	v_mfma_f32_16x16x32_bf16 v[32:35], v[194:197], v[210:213], v[32:35]
	v_mfma_f32_16x16x32_bf16 v[32:35], v[198:201], v[214:217], v[32:35]
	v_mfma_f32_16x16x32_bf16 v[28:31], v[148:151], v[218:221], v[28:31]
	v_mfma_f32_16x16x32_bf16 v[28:31], v[172:175], v[222:225], v[28:31]
	v_mfma_f32_16x16x32_bf16 v[24:27], v[176:179], v[218:221], v[24:27]
	v_mfma_f32_16x16x32_bf16 v[24:27], v[180:183], v[222:225], v[24:27]
	v_mfma_f32_16x16x32_bf16 v[20:23], v[186:189], v[218:221], v[20:23]
	v_mfma_f32_16x16x32_bf16 v[20:23], v[190:193], v[222:225], v[20:23]
	v_mfma_f32_16x16x32_bf16 v[16:19], v[194:197], v[218:221], v[16:19]
	v_mfma_f32_16x16x32_bf16 v[16:19], v[198:201], v[222:225], v[16:19]
	v_mfma_f32_16x16x32_bf16 v[12:15], v[148:151], v[226:229], v[12:15]
	v_mfma_f32_16x16x32_bf16 v[12:15], v[172:175], v[230:233], v[12:15]
	v_mfma_f32_16x16x32_bf16 v[8:11], v[176:179], v[226:229], v[8:11]
	v_mfma_f32_16x16x32_bf16 v[8:11], v[180:183], v[230:233], v[8:11]
	v_mfma_f32_16x16x32_bf16 v[4:7], v[186:189], v[226:229], v[4:7]
	v_mfma_f32_16x16x32_bf16 v[4:7], v[190:193], v[230:233], v[4:7]
	v_mfma_f32_16x16x32_bf16 v[0:3], v[194:197], v[226:229], v[0:3]
	v_mfma_f32_16x16x32_bf16 v[0:3], v[198:201], v[230:233], v[0:3]
	s_barrier
; #define PG8_STAGE(bufoff, gbase, voff) do { _Pragma("unroll") for (int _i = 0; _i < 2; ++_i) \
;         __builtin_amdgcn_global_load_lds((const unsigned*)((const char*)(gbase) + (voff)[_i]), (LAS unsigned*)(lds + (bufoff) + ldsw + _i * 8192), 16, 0, 0); } while (0)
; #define PG8_LDA(dst, b, h) do { _Pragma("unroll") for (int m = 0; m < 4; ++m) _Pragma("unroll") for (int k = 0; k < 2; ++k) dst[m][k] = *(const LAS bf16x8*)(lds + PG8_SA(b, h) + aoff + m * 2048 + k * 1024); } while (0)
; #define PG8_LDB(dst, b, h) do { _Pragma("unroll") for (int n = 0; n < 2; ++n) _Pragma("unroll") for (int k = 0; k < 2; ++k) dst[n][k] = *(const LAS bf16x8*)(lds + PG8_SB(b, h) + boff + n * 2048 + k * 1024); } while (0)
; #define PG8_MMA(ai, bj, At, Bt) do { __builtin_amdgcn_s_setprio(1); _Pragma("unroll") for (int m = 0; m < 4; ++m) _Pragma("unroll") for (int n = 0; n < 2; ++n) _Pragma("unroll") for (int k = 0; k < 2; ++k) \
;         acc[ai][bj][m][n] = __builtin_amdgcn_mfma_f32_16x16x32_bf16(Bt[n][k], At[m][k], acc[ai][bj][m][n], 0, 0, 0); __builtin_amdgcn_s_setprio(0); } while (0)
; #define PG8_WAIT_V(n) asm volatile("s_waitcnt vmcnt(" #n ")" ::: "memory")
; #define PG8_WAIT_L(n) asm volatile("s_waitcnt lgkmcnt(" #n ")" ::: "memory")
; #define PG8_BAR __builtin_amdgcn_s_barrier()
; #define PG8_SCHED __builtin_amdgcn_sched_barrier(0)
; template <bool ALIGN_EPI, class Epi, class Sched>
; __device__ __forceinline__ void gemm_phase(LAS unsigned char* lds, const int lda, const int ldb, const int K, const Sched& S, const Epi& E, const size_t kstepA = (size_t)(BK * 2), const size_t kstepB = (size_t)(BK * 2)) {
;     ...
;             PG8_LDB(B0, 1, 0); PG8_LDB(B1, 1, 1); PG8_SCHED; PG8_LDA(At, 1, 0); PG8_STAGE(PG8_SA(0, 1), a2 + hstepA, voffA);
;             PG8_WAIT_V(8); PG8_WAIT_L(0); PG8_BAR; PG8_MMA(0, 0, At, B0); PG8_MMA(0, 1, At, B1); PG8_BAR; PG8_SCHED;
;             PG8_LDA(At, 1, 1); PG8_STAGE(PG8_SB(1, 0), b3, voffB); PG8_STAGE(PG8_SB(1, 1), b3 + hstepB, voffB); PG8_STAGE(PG8_SA(1, 0), a3, voffA);
;             PG8_WAIT_V(8); PG8_WAIT_L(0); PG8_BAR; PG8_MMA(1, 0, At, B0); PG8_MMA(1, 1, At, B1); PG8_BAR; PG8_SCHED;
;         }
;         if constexpr (ALIGN_EPI) { if (wr == 0) PG8_BAR; }
	s_add_i32 s61, 0, 0x18000
	v_add_u32_e32 v136, s61, v152
	s_add_i32 s62, 0, 0x1c000
	ds_read_b128 v[148:151], v136
	ds_read_b128 v[172:175], v136 offset:1024
	ds_read_b128 v[176:179], v136 offset:2048
	ds_read_b128 v[180:183], v136 offset:3072
	v_add_u32_e32 v136, s62, v152
	ds_read_b128 v[186:189], v136
	ds_read_b128 v[190:193], v136 offset:1024
	ds_read_b128 v[194:197], v136 offset:2048
	ds_read_b128 v[198:201], v136 offset:3072
	s_add_u32 s54, s54, 0x4000
	s_addc_u32 s55, s55, 0
	s_mov_b32 m0, s31
	ds_read_b128 v[202:205], v170 offset:32768
	ds_read_b128 v[206:209], v170 offset:33792
	ds_read_b128 v[210:213], v170 offset:34816
	ds_read_b128 v[214:217], v170 offset:35840
	ds_read_b128 v[218:221], v170 offset:36864
	ds_read_b128 v[222:225], v170 offset:37888
	ds_read_b128 v[226:229], v170 offset:38912
	ds_read_b128 v[230:233], v170 offset:39936
	global_load_lds_dwordx4 v128, s[54:55]
	s_mov_b32 m0, s33
	s_nop 0
	global_load_lds_dwordx4 v132, s[54:55]
	s_waitcnt vmcnt(8)
	s_waitcnt lgkmcnt(0)
	s_barrier
	s_waitcnt lgkmcnt(0)
	v_mfma_f32_16x16x32_bf16 v[124:127], v[148:151], v[202:205], v[124:127]
	v_mfma_f32_16x16x32_bf16 v[124:127], v[172:175], v[206:209], v[124:127]
	v_mfma_f32_16x16x32_bf16 v[120:123], v[176:179], v[202:205], v[120:123]
	v_mfma_f32_16x16x32_bf16 v[120:123], v[180:183], v[206:209], v[120:123]
	v_mfma_f32_16x16x32_bf16 v[116:119], v[186:189], v[202:205], v[116:119]
	v_mfma_f32_16x16x32_bf16 v[116:119], v[190:193], v[206:209], v[116:119]
	v_mfma_f32_16x16x32_bf16 v[112:115], v[194:197], v[202:205], v[112:115]
	v_mfma_f32_16x16x32_bf16 v[112:115], v[198:201], v[206:209], v[112:115]
	v_mfma_f32_16x16x32_bf16 v[108:111], v[148:151], v[210:213], v[108:111]
	v_mfma_f32_16x16x32_bf16 v[108:111], v[172:175], v[214:217], v[108:111]
	v_mfma_f32_16x16x32_bf16 v[104:107], v[176:179], v[210:213], v[104:107]
	v_mfma_f32_16x16x32_bf16 v[104:107], v[180:183], v[214:217], v[104:107]
	v_mfma_f32_16x16x32_bf16 v[100:103], v[186:189], v[210:213], v[100:103]
	v_mfma_f32_16x16x32_bf16 v[100:103], v[190:193], v[214:217], v[100:103]
	v_mfma_f32_16x16x32_bf16 v[96:99], v[194:197], v[210:213], v[96:99]
	v_mfma_f32_16x16x32_bf16 v[96:99], v[198:201], v[214:217], v[96:99]
	v_mfma_f32_16x16x32_bf16 v[92:95], v[148:151], v[218:221], v[92:95]
	v_mfma_f32_16x16x32_bf16 v[92:95], v[172:175], v[222:225], v[92:95]
	v_mfma_f32_16x16x32_bf16 v[88:91], v[176:179], v[218:221], v[88:91]
	v_mfma_f32_16x16x32_bf16 v[88:91], v[180:183], v[222:225], v[88:91]
	v_mfma_f32_16x16x32_bf16 v[84:87], v[186:189], v[218:221], v[84:87]
	v_mfma_f32_16x16x32_bf16 v[84:87], v[190:193], v[222:225], v[84:87]
	v_mfma_f32_16x16x32_bf16 v[80:83], v[194:197], v[218:221], v[80:83]
	v_mfma_f32_16x16x32_bf16 v[80:83], v[198:201], v[222:225], v[80:83]
	v_mfma_f32_16x16x32_bf16 v[76:79], v[148:151], v[226:229], v[76:79]
	v_mfma_f32_16x16x32_bf16 v[76:79], v[172:175], v[230:233], v[76:79]
	v_mfma_f32_16x16x32_bf16 v[72:75], v[176:179], v[226:229], v[72:75]
	v_mfma_f32_16x16x32_bf16 v[72:75], v[180:183], v[230:233], v[72:75]
	v_mfma_f32_16x16x32_bf16 v[68:71], v[186:189], v[226:229], v[68:71]
	v_mfma_f32_16x16x32_bf16 v[68:71], v[190:193], v[230:233], v[68:71]
	v_mfma_f32_16x16x32_bf16 v[64:67], v[194:197], v[226:229], v[64:67]
	v_mfma_f32_16x16x32_bf16 v[64:67], v[198:201], v[230:233], v[64:67]
	s_barrier
	s_add_u32 s54, s52, 0x160000
	s_addc_u32 s55, s53, 0
	s_add_i32 s61, s61, s19
	s_mov_b32 m0, s61
	ds_read_b128 v[202:205], v170 offset:49152
	ds_read_b128 v[206:209], v170 offset:50176
	ds_read_b128 v[210:213], v170 offset:51200
	ds_read_b128 v[214:217], v170 offset:52224
	ds_read_b128 v[218:221], v170 offset:53248
	ds_read_b128 v[222:225], v170 offset:54272
	ds_read_b128 v[226:229], v170 offset:55296
	ds_read_b128 v[230:233], v170 offset:56320
	global_load_lds_dwordx4 v130, s[54:55]
	s_add_i32 m0, s61, 0x2000
	s_add_u32 s52, s52, 0x164000
	global_load_lds_dwordx4 v134, s[54:55]
	s_addc_u32 s53, s53, 0
	s_add_i32 s54, s62, s19
	s_mov_b32 m0, s54
	s_nop 0
	global_load_lds_dwordx4 v130, s[52:53]
	s_add_i32 m0, s54, 0x2000
	s_nop 0
	global_load_lds_dwordx4 v134, s[52:53]
	s_mov_b32 m0, s50
	s_nop 0
	global_load_lds_dwordx4 v128, s[48:49]
	s_mov_b32 m0, s51
	s_nop 0
	global_load_lds_dwordx4 v132, s[48:49]
	s_waitcnt vmcnt(8)
	s_waitcnt lgkmcnt(0)
	s_barrier
	s_waitcnt lgkmcnt(0)
	v_mfma_f32_16x16x32_bf16 v[60:63], v[148:151], v[202:205], v[60:63]
	v_mfma_f32_16x16x32_bf16 v[60:63], v[172:175], v[206:209], v[60:63]
	v_mfma_f32_16x16x32_bf16 v[56:59], v[176:179], v[202:205], v[56:59]
	v_mfma_f32_16x16x32_bf16 v[56:59], v[180:183], v[206:209], v[56:59]
	v_mfma_f32_16x16x32_bf16 v[52:55], v[186:189], v[202:205], v[52:55]
	v_mfma_f32_16x16x32_bf16 v[52:55], v[190:193], v[206:209], v[52:55]
	v_mfma_f32_16x16x32_bf16 v[48:51], v[194:197], v[202:205], v[48:51]
	v_mfma_f32_16x16x32_bf16 v[48:51], v[198:201], v[206:209], v[48:51]
	v_mfma_f32_16x16x32_bf16 v[44:47], v[148:151], v[210:213], v[44:47]
	v_mfma_f32_16x16x32_bf16 v[44:47], v[172:175], v[214:217], v[44:47]
	v_mfma_f32_16x16x32_bf16 v[40:43], v[176:179], v[210:213], v[40:43]
	v_mfma_f32_16x16x32_bf16 v[40:43], v[180:183], v[214:217], v[40:43]
	v_mfma_f32_16x16x32_bf16 v[36:39], v[186:189], v[210:213], v[36:39]
	v_mfma_f32_16x16x32_bf16 v[36:39], v[190:193], v[214:217], v[36:39]
	v_mfma_f32_16x16x32_bf16 v[32:35], v[194:197], v[210:213], v[32:35]
	v_mfma_f32_16x16x32_bf16 v[32:35], v[198:201], v[214:217], v[32:35]
	v_mfma_f32_16x16x32_bf16 v[28:31], v[148:151], v[218:221], v[28:31]
	v_mfma_f32_16x16x32_bf16 v[28:31], v[172:175], v[222:225], v[28:31]
	v_mfma_f32_16x16x32_bf16 v[24:27], v[176:179], v[218:221], v[24:27]
	v_mfma_f32_16x16x32_bf16 v[24:27], v[180:183], v[222:225], v[24:27]
	v_mfma_f32_16x16x32_bf16 v[20:23], v[186:189], v[218:221], v[20:23]
	v_mfma_f32_16x16x32_bf16 v[20:23], v[190:193], v[222:225], v[20:23]
	v_mfma_f32_16x16x32_bf16 v[16:19], v[194:197], v[218:221], v[16:19]
	v_mfma_f32_16x16x32_bf16 v[16:19], v[198:201], v[222:225], v[16:19]
	v_mfma_f32_16x16x32_bf16 v[12:15], v[148:151], v[226:229], v[12:15]
	v_mfma_f32_16x16x32_bf16 v[12:15], v[172:175], v[230:233], v[12:15]
	v_mfma_f32_16x16x32_bf16 v[8:11], v[176:179], v[226:229], v[8:11]
	v_mfma_f32_16x16x32_bf16 v[8:11], v[180:183], v[230:233], v[8:11]
	v_mfma_f32_16x16x32_bf16 v[4:7], v[186:189], v[226:229], v[4:7]
	v_mfma_f32_16x16x32_bf16 v[4:7], v[190:193], v[230:233], v[4:7]
	v_mfma_f32_16x16x32_bf16 v[0:3], v[194:197], v[226:229], v[0:3]
	v_mfma_f32_16x16x32_bf16 v[0:3], v[198:201], v[230:233], v[0:3]
	s_barrier
	s_add_i32 s15, s15, 2
	s_add_u32 s9, s9, 0x2c0000
	s_addc_u32 s13, s13, 0
	s_add_u32 s46, s46, 0x400000
	s_addc_u32 s47, s47, 0
	s_cmp_gt_u32 s15, 29
	s_cbranch_scc0 .LBB0_1044
	s_and_b64 vcc, exec, s[10:11]
	s_cbranch_vccz .LBB0_1047
	s_barrier

; #define PG8_STAGE(bufoff, gbase, voff) do { _Pragma("unroll") for (int _i = 0; _i < 2; ++_i) \
;         __builtin_amdgcn_global_load_lds((const unsigned*)((const char*)(gbase) + (voff)[_i]), (LAS unsigned*)(lds + (bufoff) + ldsw + _i * 8192), 16, 0, 0); } while (0)
; #define PG8_LDA(dst, b, h) do { _Pragma("unroll") for (int m = 0; m < 4; ++m) _Pragma("unroll") for (int k = 0; k < 2; ++k) dst[m][k] = *(const LAS bf16x8*)(lds + PG8_SA(b, h) + aoff + m * 2048 + k * 1024); } while (0)
; #define PG8_LDB(dst, b, h) do { _Pragma("unroll") for (int n = 0; n < 2; ++n) _Pragma("unroll") for (int k = 0; k < 2; ++k) dst[n][k] = *(const LAS bf16x8*)(lds + PG8_SB(b, h) + boff + n * 2048 + k * 1024); } while (0)
; #define PG8_MMA(ai, bj, At, Bt) do { __builtin_amdgcn_s_setprio(1); _Pragma("unroll") for (int m = 0; m < 4; ++m) _Pragma("unroll") for (int n = 0; n < 2; ++n) _Pragma("unroll") for (int k = 0; k < 2; ++k) \
;         acc[ai][bj][m][n] = __builtin_amdgcn_mfma_f32_16x16x32_bf16(Bt[n][k], At[m][k], acc[ai][bj][m][n], 0, 0, 0); __builtin_amdgcn_s_setprio(0); } while (0)
; #define PG8_WAIT_V(n) asm volatile("s_waitcnt vmcnt(" #n ")" ::: "memory")
; #define PG8_WAIT_L(n) asm volatile("s_waitcnt lgkmcnt(" #n ")" ::: "memory")
; template <bool ALIGN_EPI, class Epi, class Sched>
; __device__ __forceinline__ void gemm_phase(LAS unsigned char* lds, const int lda, const int ldb, const int K, const Sched& S, const Epi& E, const size_t kstepA = (size_t)(BK * 2), const size_t kstepB = (size_t)(BK * 2)) {
;     ...
;         for (int t = 0; t < nt; t += 2) {
;             const bool last = (t == nt - 2);
;             const char* a1 = cA + (size_t)(t + 1) * kstepA;
;             const char* a2 = last ? nA : cA + (size_t)(t + 2) * kstepA; const char* b2 = last ? nB : cB + (size_t)(t + 2) * kstep;
;             const char* a3 = a2 + kstepA; const char* b3 = b2 + kstep;
;             PG8_LDB(B0, 0, 0); PG8_LDB(B1, 0, 1); PG8_SCHED; PG8_LDA(At, 0, 0); PG8_STAGE(PG8_SA(1, 1), a1 + hstepA, voffA);
;             PG8_WAIT_V(8); PG8_WAIT_L(0); PG8_BAR; PG8_MMA(0, 0, At, B0); PG8_MMA(0, 1, At, B1); PG8_BAR; PG8_SCHED;
;             PG8_LDA(At, 0, 1); PG8_STAGE(PG8_SB(0, 0), b2, voffB); PG8_STAGE(PG8_SB(0, 1), b2 + hstepB, voffB); PG8_STAGE(PG8_SA(0, 0), a2, voffA);
;             PG8_WAIT_V(8); PG8_WAIT_L(0); PG8_BAR; PG8_MMA(1, 0, At, B0); PG8_MMA(1, 1, At, B1); PG8_BAR; PG8_SCHED;
.LBB0_1154:
	ds_read_b128 v[80:83], v219
	ds_read_b128 v[84:87], v219 offset:1024
	ds_read_b128 v[104:107], v219 offset:2048
	ds_read_b128 v[108:111], v219 offset:3072
	ds_read_b128 v[144:147], v220
	ds_read_b128 v[148:151], v220 offset:1024
	ds_read_b128 v[152:155], v220 offset:2048
	ds_read_b128 v[156:159], v220 offset:3072
	s_add_u32 s12, s10, 0x1fc000
	s_addc_u32 s13, s11, 0
	s_cmpk_eq_i32 s67, 0x54
	s_cselect_b32 s16, s0, s12
	s_cselect_b32 s17, s1, s13
	s_cselect_b32 s14, s8, s57
	s_cselect_b32 s15, s9, s59
	s_add_u32 s12, s16, 0x200000
	s_addc_u32 s13, s17, 0
	s_add_i32 m0, s19, 0xc000
	ds_read_b128 v[160:163], v221
	ds_read_b128 v[164:167], v221 offset:1024
	ds_read_b128 v[188:191], v221 offset:2048
	ds_read_b128 v[192:195], v221 offset:3072
	ds_read_b128 v[196:199], v221 offset:4096
	ds_read_b128 v[200:203], v221 offset:5120
	ds_read_b128 v[204:207], v221 offset:6144
	ds_read_b128 v[208:211], v221 offset:7168
	global_load_lds_dwordx4 v178, s[10:11]
	s_add_i32 m0, s19, 0xe000
	s_nop 0
	global_load_lds_dwordx4 v180, s[10:11]
	s_waitcnt vmcnt(8)
	s_waitcnt lgkmcnt(0)
	s_barrier
	s_waitcnt lgkmcnt(0)
	v_mfma_f32_16x16x32_bf16 v[140:143], v[80:83], v[160:163], v[140:143]
	v_mfma_f32_16x16x32_bf16 v[140:143], v[84:87], v[164:167], v[140:143]
	v_mfma_f32_16x16x32_bf16 v[136:139], v[104:107], v[160:163], v[136:139]
	v_mfma_f32_16x16x32_bf16 v[136:139], v[108:111], v[164:167], v[136:139]
	v_mfma_f32_16x16x32_bf16 v[132:135], v[144:147], v[160:163], v[132:135]
	v_mfma_f32_16x16x32_bf16 v[132:135], v[148:151], v[164:167], v[132:135]
	v_mfma_f32_16x16x32_bf16 v[128:131], v[152:155], v[160:163], v[128:131]
	v_mfma_f32_16x16x32_bf16 v[128:131], v[156:159], v[164:167], v[128:131]
	v_mfma_f32_16x16x32_bf16 v[124:127], v[80:83], v[188:191], v[124:127]
	v_mfma_f32_16x16x32_bf16 v[124:127], v[84:87], v[192:195], v[124:127]
	v_mfma_f32_16x16x32_bf16 v[120:123], v[104:107], v[188:191], v[120:123]
	v_mfma_f32_16x16x32_bf16 v[120:123], v[108:111], v[192:195], v[120:123]
	v_mfma_f32_16x16x32_bf16 v[116:119], v[144:147], v[188:191], v[116:119]
	v_mfma_f32_16x16x32_bf16 v[116:119], v[148:151], v[192:195], v[116:119]
	v_mfma_f32_16x16x32_bf16 v[112:115], v[152:155], v[188:191], v[112:115]
	v_mfma_f32_16x16x32_bf16 v[112:115], v[156:159], v[192:195], v[112:115]
	v_mfma_f32_16x16x32_bf16 v[100:103], v[80:83], v[196:199], v[100:103]
	v_mfma_f32_16x16x32_bf16 v[100:103], v[84:87], v[200:203], v[100:103]
	v_mfma_f32_16x16x32_bf16 v[96:99], v[104:107], v[196:199], v[96:99]
	v_mfma_f32_16x16x32_bf16 v[96:99], v[108:111], v[200:203], v[96:99]
	v_mfma_f32_16x16x32_bf16 v[92:95], v[144:147], v[196:199], v[92:95]
	v_mfma_f32_16x16x32_bf16 v[92:95], v[148:151], v[200:203], v[92:95]
	v_mfma_f32_16x16x32_bf16 v[88:91], v[152:155], v[196:199], v[88:91]
	v_mfma_f32_16x16x32_bf16 v[88:91], v[156:159], v[200:203], v[88:91]
	v_mfma_f32_16x16x32_bf16 v[76:79], v[80:83], v[204:207], v[76:79]
	v_mfma_f32_16x16x32_bf16 v[76:79], v[84:87], v[208:211], v[76:79]
	v_mfma_f32_16x16x32_bf16 v[72:75], v[104:107], v[204:207], v[72:75]
	v_mfma_f32_16x16x32_bf16 v[72:75], v[108:111], v[208:211], v[72:75]
	v_mfma_f32_16x16x32_bf16 v[68:71], v[144:147], v[204:207], v[68:71]
	v_mfma_f32_16x16x32_bf16 v[68:71], v[148:151], v[208:211], v[68:71]
	v_mfma_f32_16x16x32_bf16 v[64:67], v[152:155], v[204:207], v[64:67]
	v_mfma_f32_16x16x32_bf16 v[64:67], v[156:159], v[208:211], v[64:67]
	s_barrier
	s_add_i32 s68, s51, s18
	s_mov_b32 m0, s68
	ds_read_b128 v[160:163], v221 offset:16384
	ds_read_b128 v[164:167], v221 offset:17408
	ds_read_b128 v[188:191], v221 offset:18432
	ds_read_b128 v[192:195], v221 offset:19456
	ds_read_b128 v[196:199], v221 offset:20480
	ds_read_b128 v[200:203], v221 offset:21504
	ds_read_b128 v[204:207], v221 offset:22528
	ds_read_b128 v[208:211], v221 offset:23552
	global_load_lds_dwordx4 v170, s[14:15]
	s_add_i32 m0, s68, 0x2000
	s_add_u32 s68, s14, 0x4000
	s_addc_u32 s69, s15, 0
	s_add_i32 s70, s64, s18
	global_load_lds_dwordx4 v174, s[14:15]
	s_mov_b32 m0, s70
	s_nop 0
	global_load_lds_dwordx4 v170, s[68:69]
	s_add_i32 m0, s70, 0x2000
	s_nop 0
	global_load_lds_dwordx4 v174, s[68:69]
	s_mov_b32 m0, s19
	s_nop 0
	global_load_lds_dwordx4 v168, s[16:17]
	s_mov_b32 m0, s29
	s_nop 0
	global_load_lds_dwordx4 v172, s[16:17]
	s_waitcnt vmcnt(8)
	s_waitcnt lgkmcnt(0)
	s_barrier
	s_waitcnt lgkmcnt(0)
	v_mfma_f32_16x16x32_bf16 v[60:63], v[80:83], v[160:163], v[60:63]
	v_mfma_f32_16x16x32_bf16 v[60:63], v[84:87], v[164:167], v[60:63]
	v_mfma_f32_16x16x32_bf16 v[56:59], v[104:107], v[160:163], v[56:59]
	v_mfma_f32_16x16x32_bf16 v[56:59], v[108:111], v[164:167], v[56:59]
	v_mfma_f32_16x16x32_bf16 v[52:55], v[144:147], v[160:163], v[52:55]
	v_mfma_f32_16x16x32_bf16 v[52:55], v[148:151], v[164:167], v[52:55]
	v_mfma_f32_16x16x32_bf16 v[48:51], v[152:155], v[160:163], v[48:51]
	v_mfma_f32_16x16x32_bf16 v[48:51], v[156:159], v[164:167], v[48:51]
	v_mfma_f32_16x16x32_bf16 v[44:47], v[80:83], v[188:191], v[44:47]
	v_mfma_f32_16x16x32_bf16 v[44:47], v[84:87], v[192:195], v[44:47]
	v_mfma_f32_16x16x32_bf16 v[40:43], v[104:107], v[188:191], v[40:43]
	v_mfma_f32_16x16x32_bf16 v[40:43], v[108:111], v[192:195], v[40:43]
	v_mfma_f32_16x16x32_bf16 v[36:39], v[144:147], v[188:191], v[36:39]
	v_mfma_f32_16x16x32_bf16 v[36:39], v[148:151], v[192:195], v[36:39]
	v_mfma_f32_16x16x32_bf16 v[32:35], v[152:155], v[188:191], v[32:35]
	v_mfma_f32_16x16x32_bf16 v[32:35], v[156:159], v[192:195], v[32:35]
	v_mfma_f32_16x16x32_bf16 v[28:31], v[80:83], v[196:199], v[28:31]
	v_mfma_f32_16x16x32_bf16 v[28:31], v[84:87], v[200:203], v[28:31]
	v_mfma_f32_16x16x32_bf16 v[24:27], v[104:107], v[196:199], v[24:27]
	v_mfma_f32_16x16x32_bf16 v[24:27], v[108:111], v[200:203], v[24:27]
	v_mfma_f32_16x16x32_bf16 v[20:23], v[144:147], v[196:199], v[20:23]
	v_mfma_f32_16x16x32_bf16 v[20:23], v[148:151], v[200:203], v[20:23]
	v_mfma_f32_16x16x32_bf16 v[16:19], v[152:155], v[196:199], v[16:19]
	v_mfma_f32_16x16x32_bf16 v[16:19], v[156:159], v[200:203], v[16:19]
	v_mfma_f32_16x16x32_bf16 v[12:15], v[80:83], v[204:207], v[12:15]
	v_mfma_f32_16x16x32_bf16 v[12:15], v[84:87], v[208:211], v[12:15]
	v_mfma_f32_16x16x32_bf16 v[8:11], v[104:107], v[204:207], v[8:11]
	v_mfma_f32_16x16x32_bf16 v[8:11], v[108:111], v[208:211], v[8:11]
	v_mfma_f32_16x16x32_bf16 v[4:7], v[144:147], v[204:207], v[4:7]
	v_mfma_f32_16x16x32_bf16 v[4:7], v[148:151], v[208:211], v[4:7]
	v_mfma_f32_16x16x32_bf16 v[0:3], v[152:155], v[204:207], v[0:3]
	v_mfma_f32_16x16x32_bf16 v[0:3], v[156:159], v[208:211], v[0:3]
	s_barrier
; #define PG8_STAGE(bufoff, gbase, voff) do { _Pragma("unroll") for (int _i = 0; _i < 2; ++_i) \
;         __builtin_amdgcn_global_load_lds((const unsigned*)((const char*)(gbase) + (voff)[_i]), (LAS unsigned*)(lds + (bufoff) + ldsw + _i * 8192), 16, 0, 0); } while (0)
; #define PG8_LDA(dst, b, h) do { _Pragma("unroll") for (int m = 0; m < 4; ++m) _Pragma("unroll") for (int k = 0; k < 2; ++k) dst[m][k] = *(const LAS bf16x8*)(lds + PG8_SA(b, h) + aoff + m * 2048 + k * 1024); } while (0)
; #define PG8_LDB(dst, b, h) do { _Pragma("unroll") for (int n = 0; n < 2; ++n) _Pragma("unroll") for (int k = 0; k < 2; ++k) dst[n][k] = *(const LAS bf16x8*)(lds + PG8_SB(b, h) + boff + n * 2048 + k * 1024); } while (0)
; #define PG8_MMA(ai, bj, At, Bt) do { __builtin_amdgcn_s_setprio(1); _Pragma("unroll") for (int m = 0; m < 4; ++m) _Pragma("unroll") for (int n = 0; n < 2; ++n) _Pragma("unroll") for (int k = 0; k < 2; ++k) \
;         acc[ai][bj][m][n] = __builtin_amdgcn_mfma_f32_16x16x32_bf16(Bt[n][k], At[m][k], acc[ai][bj][m][n], 0, 0, 0); __builtin_amdgcn_s_setprio(0); } while (0)
; #define PG8_WAIT_V(n) asm volatile("s_waitcnt vmcnt(" #n ")" ::: "memory")
; #define PG8_WAIT_L(n) asm volatile("s_waitcnt lgkmcnt(" #n ")" ::: "memory")
; #define PG8_BAR __builtin_amdgcn_s_barrier()
; #define PG8_SCHED __builtin_amdgcn_sched_barrier(0)
; template <bool ALIGN_EPI, class Epi, class Sched>
; __device__ __forceinline__ void gemm_phase(LAS unsigned char* lds, const int lda, const int ldb, const int K, const Sched& S, const Epi& E, const size_t kstepA = (size_t)(BK * 2), const size_t kstepB = (size_t)(BK * 2)) {
;     ...
;             PG8_LDB(B0, 1, 0); PG8_LDB(B1, 1, 1); PG8_SCHED; PG8_LDA(At, 1, 0); PG8_STAGE(PG8_SA(0, 1), a2 + hstepA, voffA);
;             PG8_WAIT_V(8); PG8_WAIT_L(0); PG8_BAR; PG8_MMA(0, 0, At, B0); PG8_MMA(0, 1, At, B1); PG8_BAR; PG8_SCHED;
;             PG8_LDA(At, 1, 1); PG8_STAGE(PG8_SB(1, 0), b3, voffB); PG8_STAGE(PG8_SB(1, 1), b3 + hstepB, voffB); PG8_STAGE(PG8_SA(1, 0), a3, voffA);
;             PG8_WAIT_V(8); PG8_WAIT_L(0); PG8_BAR; PG8_MMA(1, 0, At, B0); PG8_MMA(1, 1, At, B1); PG8_BAR; PG8_SCHED;
;         }
;         if constexpr (ALIGN_EPI) { if (wr == 0) PG8_BAR; }
	s_add_i32 s68, 0, 0x18000
	s_add_i32 s69, 0, 0x1c000
	v_add_u32_e32 v108, s68, v218
	v_add_u32_e32 v156, s69, v218
	ds_read_b128 v[80:83], v108
	ds_read_b128 v[84:87], v108 offset:1024
	ds_read_b128 v[104:107], v108 offset:2048
	ds_read_b128 v[108:111], v108 offset:3072
	ds_read_b128 v[144:147], v156
	ds_read_b128 v[148:151], v156 offset:1024
	ds_read_b128 v[152:155], v156 offset:2048
	ds_read_b128 v[156:159], v156 offset:3072
	s_add_u32 s16, s16, 0x4000
	s_addc_u32 s17, s17, 0
	s_mov_b32 m0, s30
	ds_read_b128 v[160:163], v221 offset:32768
	ds_read_b128 v[164:167], v221 offset:33792
	ds_read_b128 v[188:191], v221 offset:34816
	ds_read_b128 v[192:195], v221 offset:35840
	ds_read_b128 v[196:199], v221 offset:36864
	ds_read_b128 v[200:203], v221 offset:37888
	ds_read_b128 v[204:207], v221 offset:38912
	ds_read_b128 v[208:211], v221 offset:39936
	global_load_lds_dwordx4 v168, s[16:17]
	s_mov_b32 m0, s31
	s_nop 0
	global_load_lds_dwordx4 v172, s[16:17]
	s_waitcnt vmcnt(8)
	s_waitcnt lgkmcnt(0)
	s_barrier
	s_waitcnt lgkmcnt(0)
	v_mfma_f32_16x16x32_bf16 v[140:143], v[80:83], v[160:163], v[140:143]
	v_mfma_f32_16x16x32_bf16 v[140:143], v[84:87], v[164:167], v[140:143]
	v_mfma_f32_16x16x32_bf16 v[136:139], v[104:107], v[160:163], v[136:139]
	v_mfma_f32_16x16x32_bf16 v[136:139], v[108:111], v[164:167], v[136:139]
	v_mfma_f32_16x16x32_bf16 v[132:135], v[144:147], v[160:163], v[132:135]
	v_mfma_f32_16x16x32_bf16 v[132:135], v[148:151], v[164:167], v[132:135]
	v_mfma_f32_16x16x32_bf16 v[128:131], v[152:155], v[160:163], v[128:131]
	v_mfma_f32_16x16x32_bf16 v[128:131], v[156:159], v[164:167], v[128:131]
	v_mfma_f32_16x16x32_bf16 v[124:127], v[80:83], v[188:191], v[124:127]
	v_mfma_f32_16x16x32_bf16 v[124:127], v[84:87], v[192:195], v[124:127]
	v_mfma_f32_16x16x32_bf16 v[120:123], v[104:107], v[188:191], v[120:123]
	v_mfma_f32_16x16x32_bf16 v[120:123], v[108:111], v[192:195], v[120:123]
	v_mfma_f32_16x16x32_bf16 v[116:119], v[144:147], v[188:191], v[116:119]
	v_mfma_f32_16x16x32_bf16 v[116:119], v[148:151], v[192:195], v[116:119]
	v_mfma_f32_16x16x32_bf16 v[112:115], v[152:155], v[188:191], v[112:115]
	v_mfma_f32_16x16x32_bf16 v[112:115], v[156:159], v[192:195], v[112:115]
	v_mfma_f32_16x16x32_bf16 v[100:103], v[80:83], v[196:199], v[100:103]
	v_mfma_f32_16x16x32_bf16 v[100:103], v[84:87], v[200:203], v[100:103]
	v_mfma_f32_16x16x32_bf16 v[96:99], v[104:107], v[196:199], v[96:99]
	v_mfma_f32_16x16x32_bf16 v[96:99], v[108:111], v[200:203], v[96:99]
	v_mfma_f32_16x16x32_bf16 v[92:95], v[144:147], v[196:199], v[92:95]
	v_mfma_f32_16x16x32_bf16 v[92:95], v[148:151], v[200:203], v[92:95]
	v_mfma_f32_16x16x32_bf16 v[88:91], v[152:155], v[196:199], v[88:91]
	v_mfma_f32_16x16x32_bf16 v[88:91], v[156:159], v[200:203], v[88:91]
	v_mfma_f32_16x16x32_bf16 v[76:79], v[80:83], v[204:207], v[76:79]
	v_mfma_f32_16x16x32_bf16 v[76:79], v[84:87], v[208:211], v[76:79]
	v_mfma_f32_16x16x32_bf16 v[72:75], v[104:107], v[204:207], v[72:75]
	v_mfma_f32_16x16x32_bf16 v[72:75], v[108:111], v[208:211], v[72:75]
	v_mfma_f32_16x16x32_bf16 v[68:71], v[144:147], v[204:207], v[68:71]
	v_mfma_f32_16x16x32_bf16 v[68:71], v[148:151], v[208:211], v[68:71]
	v_mfma_f32_16x16x32_bf16 v[64:67], v[152:155], v[204:207], v[64:67]
	v_mfma_f32_16x16x32_bf16 v[64:67], v[156:159], v[208:211], v[64:67]
	s_barrier
	s_add_u32 s16, s14, 0x40000
	s_addc_u32 s17, s15, 0
	s_add_i32 s68, s68, s18
	s_mov_b32 m0, s68
	ds_read_b128 v[160:163], v221 offset:49152
	ds_read_b128 v[164:167], v221 offset:50176
	ds_read_b128 v[188:191], v221 offset:51200
	ds_read_b128 v[192:195], v221 offset:52224
	ds_read_b128 v[196:199], v221 offset:53248
	ds_read_b128 v[200:203], v221 offset:54272
	ds_read_b128 v[204:207], v221 offset:55296
	ds_read_b128 v[208:211], v221 offset:56320
	global_load_lds_dwordx4 v170, s[16:17]
	s_add_i32 m0, s68, 0x2000
	s_add_u32 s14, s14, 0x44000
	global_load_lds_dwordx4 v174, s[16:17]
	s_addc_u32 s15, s15, 0
	s_add_i32 s16, s69, s18
	s_mov_b32 m0, s16
	s_nop 0
	global_load_lds_dwordx4 v170, s[14:15]
	s_add_i32 m0, s16, 0x2000
	s_nop 0
	global_load_lds_dwordx4 v174, s[14:15]
	s_mov_b32 m0, s43
	s_nop 0
	global_load_lds_dwordx4 v168, s[12:13]
	s_mov_b32 m0, s50
	s_nop 0
	global_load_lds_dwordx4 v172, s[12:13]
	s_waitcnt vmcnt(8)
	s_waitcnt lgkmcnt(0)
	s_barrier
	s_waitcnt lgkmcnt(0)
	v_mfma_f32_16x16x32_bf16 v[60:63], v[80:83], v[160:163], v[60:63]
	v_mfma_f32_16x16x32_bf16 v[60:63], v[84:87], v[164:167], v[60:63]
	v_mfma_f32_16x16x32_bf16 v[56:59], v[104:107], v[160:163], v[56:59]
	v_mfma_f32_16x16x32_bf16 v[56:59], v[108:111], v[164:167], v[56:59]
	v_mfma_f32_16x16x32_bf16 v[52:55], v[144:147], v[160:163], v[52:55]
	v_mfma_f32_16x16x32_bf16 v[52:55], v[148:151], v[164:167], v[52:55]
	v_mfma_f32_16x16x32_bf16 v[48:51], v[152:155], v[160:163], v[48:51]
	v_mfma_f32_16x16x32_bf16 v[48:51], v[156:159], v[164:167], v[48:51]
	v_mfma_f32_16x16x32_bf16 v[44:47], v[80:83], v[188:191], v[44:47]
	v_mfma_f32_16x16x32_bf16 v[44:47], v[84:87], v[192:195], v[44:47]
	v_mfma_f32_16x16x32_bf16 v[40:43], v[104:107], v[188:191], v[40:43]
	v_mfma_f32_16x16x32_bf16 v[40:43], v[108:111], v[192:195], v[40:43]
	v_mfma_f32_16x16x32_bf16 v[36:39], v[144:147], v[188:191], v[36:39]
	v_mfma_f32_16x16x32_bf16 v[36:39], v[148:151], v[192:195], v[36:39]
	v_mfma_f32_16x16x32_bf16 v[32:35], v[152:155], v[188:191], v[32:35]
	v_mfma_f32_16x16x32_bf16 v[32:35], v[156:159], v[192:195], v[32:35]
	v_mfma_f32_16x16x32_bf16 v[28:31], v[80:83], v[196:199], v[28:31]
	v_mfma_f32_16x16x32_bf16 v[28:31], v[84:87], v[200:203], v[28:31]
	v_mfma_f32_16x16x32_bf16 v[24:27], v[104:107], v[196:199], v[24:27]
	v_mfma_f32_16x16x32_bf16 v[24:27], v[108:111], v[200:203], v[24:27]
	v_mfma_f32_16x16x32_bf16 v[20:23], v[144:147], v[196:199], v[20:23]
	v_mfma_f32_16x16x32_bf16 v[20:23], v[148:151], v[200:203], v[20:23]
	v_mfma_f32_16x16x32_bf16 v[16:19], v[152:155], v[196:199], v[16:19]
	v_mfma_f32_16x16x32_bf16 v[16:19], v[156:159], v[200:203], v[16:19]
	v_mfma_f32_16x16x32_bf16 v[12:15], v[80:83], v[204:207], v[12:15]
	v_mfma_f32_16x16x32_bf16 v[12:15], v[84:87], v[208:211], v[12:15]
	v_mfma_f32_16x16x32_bf16 v[8:11], v[104:107], v[204:207], v[8:11]
	v_mfma_f32_16x16x32_bf16 v[8:11], v[108:111], v[208:211], v[8:11]
	v_mfma_f32_16x16x32_bf16 v[4:7], v[144:147], v[204:207], v[4:7]
	v_mfma_f32_16x16x32_bf16 v[4:7], v[148:151], v[208:211], v[4:7]
	v_mfma_f32_16x16x32_bf16 v[0:3], v[152:155], v[204:207], v[0:3]
	v_mfma_f32_16x16x32_bf16 v[0:3], v[156:159], v[208:211], v[0:3]
	s_barrier
	s_add_i32 s67, s67, 2
	s_add_u32 s57, s57, 0x80000
	s_addc_u32 s59, s59, 0
	s_add_u32 s10, s10, 0x400000
	s_addc_u32 s11, s11, 0
	s_cmpk_gt_u32 s67, 0x55
	s_cbranch_scc0 .LBB0_1154
	s_and_b64 vcc, exec, s[46:47]
	s_cbranch_vccz .LBB0_1157
	s_barrier
